# MFMA order k-inner: the two k-steps of each accumulator issued back to back (all four GEMM K-loops)
# speedup vs baseline: 1.0133x; 1.0133x over previous
; #define PG8_STAGE(bufoff, gbase, voff) do { _Pragma("unroll") for (int _i = 0; _i < 2; ++_i) \
;         __builtin_amdgcn_global_load_lds((const unsigned*)((const char*)(gbase) + (voff)[_i]), (PG8_LAS unsigned*)(lds + (bufoff) + ldsw + _i * 8192), 16, 0, 0); } while (0)
; #define PG8_LDA(dst, b, h) do { _Pragma("unroll") for (int m = 0; m < 4; ++m) _Pragma("unroll") for (int k = 0; k < 2; ++k) dst[m][k] = *(const PG8_LAS bf16x8*)(lds + PG8_SA(b, h) + aoff + m * 2048 + k * 1024); } while (0)
; #define PG8_LDB(dst, b, h) do { _Pragma("unroll") for (int n = 0; n < 2; ++n) _Pragma("unroll") for (int k = 0; k < 2; ++k) dst[n][k] = *(const PG8_LAS bf16x8*)(lds + PG8_SB(b, h) + boff + n * 2048 + k * 1024); } while (0)
; #define PG8_MMA(ai, bj, At, Bt) do { __builtin_amdgcn_s_setprio(1); _Pragma("unroll") for (int m = 0; m < 4; ++m) _Pragma("unroll") for (int n = 0; n < 2; ++n) _Pragma("unroll") for (int k = 0; k < 2; ++k) \
;         acc[ai][bj][m][n] = __builtin_amdgcn_mfma_f32_16x16x32_bf16(Bt[n][k], At[m][k], acc[ai][bj][m][n], 0, 0, 0); __builtin_amdgcn_s_setprio(0); } while (0)
; #define PG8_WAIT_V(n) asm volatile("s_waitcnt vmcnt(" #n ")" ::: "memory")
; #define PG8_WAIT_L(n) asm volatile("s_waitcnt lgkmcnt(" #n ")" ::: "memory")
; #define PG8_BAR __builtin_amdgcn_s_barrier()
; #define PG8_SCHED __builtin_amdgcn_sched_barrier(0)
; template <class Epi, class Sched, bool ALIGN_EPI = false, bool SP2 = false>
; __device__ __forceinline__ void gemm_phase(PG8_LAS unsigned char* lds, const Gemm g, const Sched& S, const Epi& E) {
;     ...
;             PG8_LDB(B0, 0, 0); PG8_LDB(B1, 0, 1); PG8_SCHED; PG8_LDA(At, 0, 0); PG8_STAGE(PG8_SA(1, 1), a1 + hstep, voffA);
;             PG8_WAIT_V(8); PG8_WAIT_L(0); PG8_BAR; PG8_MMA(0, 0, At, B0); PG8_MMA(0, 1, At, B1); PG8_BAR; PG8_SCHED;
;             PG8_LDA(At, 0, 1); PG8_STAGE(PG8_SB(0, 0), b2, voffB); PG8_STAGE(PG8_SB(0, 1), b2 + hstepB, voffB); PG8_STAGE(PG8_SA(0, 0), a2, voffA);
;             PG8_WAIT_V(8); PG8_WAIT_L(0); PG8_BAR; PG8_MMA(1, 0, At, B0); PG8_MMA(1, 1, At, B1); PG8_BAR; PG8_SCHED;
.LBB0_402:
	ds_read_b128 v[82:85], v178
	ds_read_b128 v[86:89], v178 offset:1024
	ds_read_b128 v[90:93], v178 offset:2048
	ds_read_b128 v[94:97], v178 offset:3072
	ds_read_b128 v[186:189], v179
	ds_read_b128 v[190:193], v179 offset:1024
	ds_read_b128 v[194:197], v179 offset:2048
	ds_read_b128 v[198:201], v179 offset:3072
	s_add_u32 s10, s6, 0xfff00080
	s_addc_u32 s11, s7, -1
	s_cmp_eq_u32 s51, 60
	s_cselect_b32 s35, s23, s11
	s_cselect_b32 s34, s47, s10
	s_cselect_b32 s11, s21, s50
	s_cselect_b32 s10, s48, s49
	v_lshl_add_u64 v[234:235], s[6:7], 0, v[158:159]
	s_add_i32 m0, s29, 0xc000
	ds_read_b128 v[202:205], v180
	ds_read_b128 v[206:209], v180 offset:1024
	ds_read_b128 v[210:213], v180 offset:2048
	ds_read_b128 v[214:217], v180 offset:3072
	ds_read_b128 v[218:221], v180 offset:4096
	ds_read_b128 v[222:225], v180 offset:5120
	ds_read_b128 v[226:229], v180 offset:6144
	ds_read_b128 v[230:233], v180 offset:7168
	global_load_lds_dwordx4 v[234:235], off
	v_lshl_add_u64 v[234:235], s[6:7], 0, v[160:161]
	s_add_i32 m0, s29, 0xe000
	s_nop 0
	global_load_lds_dwordx4 v[234:235], off
	s_waitcnt vmcnt(8)
	s_waitcnt lgkmcnt(0)
	s_barrier
	s_setprio 1
	s_waitcnt lgkmcnt(0)
	v_mfma_f32_16x16x32_bf16 v[142:145], v[82:85], v[202:205], v[142:145]
	v_mfma_f32_16x16x32_bf16 v[142:145], v[86:89], v[206:209], v[142:145]
	v_mfma_f32_16x16x32_bf16 v[138:141], v[90:93], v[202:205], v[138:141]
	v_mfma_f32_16x16x32_bf16 v[138:141], v[94:97], v[206:209], v[138:141]
	v_mfma_f32_16x16x32_bf16 v[126:129], v[82:85], v[210:213], v[126:129]
	v_mfma_f32_16x16x32_bf16 v[126:129], v[86:89], v[214:217], v[126:129]
	v_mfma_f32_16x16x32_bf16 v[122:125], v[90:93], v[210:213], v[122:125]
	v_mfma_f32_16x16x32_bf16 v[122:125], v[94:97], v[214:217], v[122:125]
	v_mfma_f32_16x16x32_bf16 v[110:113], v[82:85], v[218:221], v[110:113]
	v_mfma_f32_16x16x32_bf16 v[110:113], v[86:89], v[222:225], v[110:113]
	v_mfma_f32_16x16x32_bf16 v[106:109], v[90:93], v[218:221], v[106:109]
	v_mfma_f32_16x16x32_bf16 v[106:109], v[94:97], v[222:225], v[106:109]
	v_mfma_f32_16x16x32_bf16 v[78:81], v[82:85], v[226:229], v[78:81]
	v_mfma_f32_16x16x32_bf16 v[78:81], v[86:89], v[230:233], v[78:81]
	v_mfma_f32_16x16x32_bf16 v[74:77], v[90:93], v[226:229], v[74:77]
	v_mfma_f32_16x16x32_bf16 v[74:77], v[94:97], v[230:233], v[74:77]
	s_setprio 0
	s_setprio 1
	v_mfma_f32_16x16x32_bf16 v[134:137], v[186:189], v[202:205], v[134:137]
	v_mfma_f32_16x16x32_bf16 v[134:137], v[190:193], v[206:209], v[134:137]
	v_mfma_f32_16x16x32_bf16 v[130:133], v[194:197], v[202:205], v[130:133]
	v_mfma_f32_16x16x32_bf16 v[130:133], v[198:201], v[206:209], v[130:133]
	v_mfma_f32_16x16x32_bf16 v[118:121], v[186:189], v[210:213], v[118:121]
	v_mfma_f32_16x16x32_bf16 v[118:121], v[190:193], v[214:217], v[118:121]
	v_mfma_f32_16x16x32_bf16 v[114:117], v[194:197], v[210:213], v[114:117]
	v_mfma_f32_16x16x32_bf16 v[114:117], v[198:201], v[214:217], v[114:117]
	v_mfma_f32_16x16x32_bf16 v[102:105], v[186:189], v[218:221], v[102:105]
	v_mfma_f32_16x16x32_bf16 v[102:105], v[190:193], v[222:225], v[102:105]
	v_mfma_f32_16x16x32_bf16 v[98:101], v[194:197], v[218:221], v[98:101]
	v_mfma_f32_16x16x32_bf16 v[98:101], v[198:201], v[222:225], v[98:101]
	v_mfma_f32_16x16x32_bf16 v[70:73], v[186:189], v[226:229], v[70:73]
	v_mfma_f32_16x16x32_bf16 v[70:73], v[190:193], v[230:233], v[70:73]
	v_mfma_f32_16x16x32_bf16 v[66:69], v[194:197], v[226:229], v[66:69]
	v_mfma_f32_16x16x32_bf16 v[66:69], v[198:201], v[230:233], v[66:69]
	s_setprio 0
	s_barrier
	s_add_i32 s52, s42, s37
	v_lshl_add_u64 v[234:235], s[10:11], 0, v[148:149]
	s_mov_b32 m0, s52
	ds_read_b128 v[202:205], v180 offset:16384
	ds_read_b128 v[206:209], v180 offset:17408
	ds_read_b128 v[210:213], v180 offset:18432
	ds_read_b128 v[214:217], v180 offset:19456
	ds_read_b128 v[218:221], v180 offset:20480
	ds_read_b128 v[222:225], v180 offset:21504
	ds_read_b128 v[226:229], v180 offset:22528
	ds_read_b128 v[230:233], v180 offset:23552
	global_load_lds_dwordx4 v[234:235], off
	s_add_i32 m0, s52, 0x2000
	s_add_u32 s52, s10, 0x40000
	v_lshl_add_u64 v[236:237], s[10:11], 0, v[152:153]
	s_addc_u32 s53, s11, 0
	s_add_i32 s54, s43, s37
	global_load_lds_dwordx4 v[236:237], off
	v_lshl_add_u64 v[238:239], s[52:53], 0, v[148:149]
	s_mov_b32 m0, s54
	v_lshl_add_u64 v[240:241], s[34:35], 0, v[150:151]
	global_load_lds_dwordx4 v[238:239], off
	v_lshl_add_u64 v[238:239], s[52:53], 0, v[152:153]
	s_add_i32 m0, s54, 0x2000
	s_nop 0
	global_load_lds_dwordx4 v[238:239], off
	v_lshl_add_u64 v[238:239], s[34:35], 0, v[146:147]
	s_mov_b32 m0, s29
	s_nop 0
	global_load_lds_dwordx4 v[238:239], off
	s_mov_b32 m0, s31
	s_nop 0
	global_load_lds_dwordx4 v[240:241], off
	s_waitcnt vmcnt(8)
	s_waitcnt lgkmcnt(0)
	s_barrier
; #define PG8_STAGE(bufoff, gbase, voff) do { _Pragma("unroll") for (int _i = 0; _i < 2; ++_i) \
;         __builtin_amdgcn_global_load_lds((const unsigned*)((const char*)(gbase) + (voff)[_i]), (PG8_LAS unsigned*)(lds + (bufoff) + ldsw + _i * 8192), 16, 0, 0); } while (0)
; #define PG8_LDA(dst, b, h) do { _Pragma("unroll") for (int m = 0; m < 4; ++m) _Pragma("unroll") for (int k = 0; k < 2; ++k) dst[m][k] = *(const PG8_LAS bf16x8*)(lds + PG8_SA(b, h) + aoff + m * 2048 + k * 1024); } while (0)
; #define PG8_LDB(dst, b, h) do { _Pragma("unroll") for (int n = 0; n < 2; ++n) _Pragma("unroll") for (int k = 0; k < 2; ++k) dst[n][k] = *(const PG8_LAS bf16x8*)(lds + PG8_SB(b, h) + boff + n * 2048 + k * 1024); } while (0)
; #define PG8_MMA(ai, bj, At, Bt) do { __builtin_amdgcn_s_setprio(1); _Pragma("unroll") for (int m = 0; m < 4; ++m) _Pragma("unroll") for (int n = 0; n < 2; ++n) _Pragma("unroll") for (int k = 0; k < 2; ++k) \
;         acc[ai][bj][m][n] = __builtin_amdgcn_mfma_f32_16x16x32_bf16(Bt[n][k], At[m][k], acc[ai][bj][m][n], 0, 0, 0); __builtin_amdgcn_s_setprio(0); } while (0)
; #define PG8_WAIT_V(n) asm volatile("s_waitcnt vmcnt(" #n ")" ::: "memory")
; #define PG8_WAIT_L(n) asm volatile("s_waitcnt lgkmcnt(" #n ")" ::: "memory")
; #define PG8_BAR __builtin_amdgcn_s_barrier()
; #define PG8_SCHED __builtin_amdgcn_sched_barrier(0)
; template <class Epi, class Sched, bool ALIGN_EPI = false, bool SP2 = false>
; __device__ __forceinline__ void gemm_phase(PG8_LAS unsigned char* lds, const Gemm g, const Sched& S, const Epi& E) {
;     ...
;             PG8_WAIT_V(8); PG8_WAIT_L(0); PG8_BAR; PG8_MMA(1, 0, At, B0); PG8_MMA(1, 1, At, B1); PG8_BAR; PG8_SCHED;
;             PG8_LDB(B0, 1, 0); PG8_LDB(B1, 1, 1); PG8_SCHED; PG8_LDA(At, 1, 0); PG8_STAGE(PG8_SA(0, 1), a2 + hstep, voffA);
;             PG8_WAIT_V(8); PG8_WAIT_L(0); PG8_BAR; PG8_MMA(0, 0, At, B0); PG8_MMA(0, 1, At, B1); PG8_BAR; PG8_SCHED;
	s_setprio 1
	s_waitcnt lgkmcnt(0)
	v_mfma_f32_16x16x32_bf16 v[62:65], v[82:85], v[202:205], v[62:65]
	v_mfma_f32_16x16x32_bf16 v[62:65], v[86:89], v[206:209], v[62:65]
	v_mfma_f32_16x16x32_bf16 v[58:61], v[90:93], v[202:205], v[58:61]
	v_mfma_f32_16x16x32_bf16 v[58:61], v[94:97], v[206:209], v[58:61]
	v_mfma_f32_16x16x32_bf16 v[46:49], v[82:85], v[210:213], v[46:49]
	v_mfma_f32_16x16x32_bf16 v[46:49], v[86:89], v[214:217], v[46:49]
	v_mfma_f32_16x16x32_bf16 v[42:45], v[90:93], v[210:213], v[42:45]
	v_mfma_f32_16x16x32_bf16 v[42:45], v[94:97], v[214:217], v[42:45]
	v_mfma_f32_16x16x32_bf16 v[30:33], v[82:85], v[218:221], v[30:33]
	v_mfma_f32_16x16x32_bf16 v[30:33], v[86:89], v[222:225], v[30:33]
	v_mfma_f32_16x16x32_bf16 v[26:29], v[90:93], v[218:221], v[26:29]
	v_mfma_f32_16x16x32_bf16 v[26:29], v[94:97], v[222:225], v[26:29]
	v_mfma_f32_16x16x32_bf16 v[14:17], v[82:85], v[226:229], v[14:17]
	v_mfma_f32_16x16x32_bf16 v[14:17], v[86:89], v[230:233], v[14:17]
	v_mfma_f32_16x16x32_bf16 v[10:13], v[90:93], v[226:229], v[10:13]
	v_mfma_f32_16x16x32_bf16 v[10:13], v[94:97], v[230:233], v[10:13]
	s_setprio 0
	s_setprio 1
	v_mfma_f32_16x16x32_bf16 v[54:57], v[186:189], v[202:205], v[54:57]
	v_mfma_f32_16x16x32_bf16 v[54:57], v[190:193], v[206:209], v[54:57]
	v_mfma_f32_16x16x32_bf16 v[50:53], v[194:197], v[202:205], v[50:53]
	v_mfma_f32_16x16x32_bf16 v[50:53], v[198:201], v[206:209], v[50:53]
	v_mfma_f32_16x16x32_bf16 v[38:41], v[186:189], v[210:213], v[38:41]
	v_mfma_f32_16x16x32_bf16 v[38:41], v[190:193], v[214:217], v[38:41]
	v_mfma_f32_16x16x32_bf16 v[34:37], v[194:197], v[210:213], v[34:37]
	v_mfma_f32_16x16x32_bf16 v[34:37], v[198:201], v[214:217], v[34:37]
	v_mfma_f32_16x16x32_bf16 v[22:25], v[186:189], v[218:221], v[22:25]
	v_mfma_f32_16x16x32_bf16 v[22:25], v[190:193], v[222:225], v[22:25]
	v_mfma_f32_16x16x32_bf16 v[18:21], v[194:197], v[218:221], v[18:21]
	v_mfma_f32_16x16x32_bf16 v[18:21], v[198:201], v[222:225], v[18:21]
	v_mfma_f32_16x16x32_bf16 v[6:9], v[186:189], v[226:229], v[6:9]
	v_mfma_f32_16x16x32_bf16 v[6:9], v[190:193], v[230:233], v[6:9]
	v_mfma_f32_16x16x32_bf16 v[2:5], v[194:197], v[226:229], v[2:5]
	v_mfma_f32_16x16x32_bf16 v[2:5], v[198:201], v[230:233], v[2:5]
	s_setprio 0
	s_barrier
	s_add_i32 s52, 0, 0x18000
	s_add_i32 s53, 0, 0x1c000
	v_add_u32_e32 v94, s52, v1
	v_add_u32_e32 v167, s53, v1
	ds_read_b128 v[82:85], v94
	ds_read_b128 v[86:89], v94 offset:1024
	ds_read_b128 v[90:93], v94 offset:2048
	ds_read_b128 v[94:97], v94 offset:3072
	ds_read_b128 v[186:189], v167
	ds_read_b128 v[190:193], v167 offset:1024
	ds_read_b128 v[194:197], v167 offset:2048
	ds_read_b128 v[198:201], v167 offset:3072
	s_add_u32 s34, s34, 0x100000
	s_addc_u32 s35, s35, 0
	s_mov_b32 m0, s38
	v_lshl_add_u64 v[242:243], s[34:35], 0, v[146:147]
	ds_read_b128 v[202:205], v180 offset:32768
	ds_read_b128 v[206:209], v180 offset:33792
	ds_read_b128 v[210:213], v180 offset:34816
	ds_read_b128 v[214:217], v180 offset:35840
	ds_read_b128 v[218:221], v180 offset:36864
	ds_read_b128 v[222:225], v180 offset:37888
	ds_read_b128 v[226:229], v180 offset:38912
	ds_read_b128 v[230:233], v180 offset:39936
	global_load_lds_dwordx4 v[242:243], off
	v_lshl_add_u64 v[242:243], s[34:35], 0, v[150:151]
	s_mov_b32 m0, s39
	s_nop 0
	global_load_lds_dwordx4 v[242:243], off
	s_waitcnt vmcnt(8)
	s_waitcnt lgkmcnt(0)
	s_barrier
	s_setprio 1
	s_waitcnt lgkmcnt(0)
	v_mfma_f32_16x16x32_bf16 v[142:145], v[82:85], v[202:205], v[142:145]
	v_mfma_f32_16x16x32_bf16 v[142:145], v[86:89], v[206:209], v[142:145]
	v_mfma_f32_16x16x32_bf16 v[138:141], v[90:93], v[202:205], v[138:141]
	v_mfma_f32_16x16x32_bf16 v[138:141], v[94:97], v[206:209], v[138:141]
	v_mfma_f32_16x16x32_bf16 v[126:129], v[82:85], v[210:213], v[126:129]
	v_mfma_f32_16x16x32_bf16 v[126:129], v[86:89], v[214:217], v[126:129]
	v_mfma_f32_16x16x32_bf16 v[122:125], v[90:93], v[210:213], v[122:125]
	v_mfma_f32_16x16x32_bf16 v[122:125], v[94:97], v[214:217], v[122:125]
	v_mfma_f32_16x16x32_bf16 v[110:113], v[82:85], v[218:221], v[110:113]
	v_mfma_f32_16x16x32_bf16 v[110:113], v[86:89], v[222:225], v[110:113]
	v_mfma_f32_16x16x32_bf16 v[106:109], v[90:93], v[218:221], v[106:109]
	v_mfma_f32_16x16x32_bf16 v[106:109], v[94:97], v[222:225], v[106:109]
	v_mfma_f32_16x16x32_bf16 v[78:81], v[82:85], v[226:229], v[78:81]
	v_mfma_f32_16x16x32_bf16 v[78:81], v[86:89], v[230:233], v[78:81]
	v_mfma_f32_16x16x32_bf16 v[74:77], v[90:93], v[226:229], v[74:77]
	v_mfma_f32_16x16x32_bf16 v[74:77], v[94:97], v[230:233], v[74:77]
	s_setprio 0
	s_setprio 1
	v_mfma_f32_16x16x32_bf16 v[134:137], v[186:189], v[202:205], v[134:137]
	v_mfma_f32_16x16x32_bf16 v[134:137], v[190:193], v[206:209], v[134:137]
	v_mfma_f32_16x16x32_bf16 v[130:133], v[194:197], v[202:205], v[130:133]
	v_mfma_f32_16x16x32_bf16 v[130:133], v[198:201], v[206:209], v[130:133]
	v_mfma_f32_16x16x32_bf16 v[118:121], v[186:189], v[210:213], v[118:121]
	v_mfma_f32_16x16x32_bf16 v[118:121], v[190:193], v[214:217], v[118:121]
	v_mfma_f32_16x16x32_bf16 v[114:117], v[194:197], v[210:213], v[114:117]
	v_mfma_f32_16x16x32_bf16 v[114:117], v[198:201], v[214:217], v[114:117]
	v_mfma_f32_16x16x32_bf16 v[102:105], v[186:189], v[218:221], v[102:105]
	v_mfma_f32_16x16x32_bf16 v[102:105], v[190:193], v[222:225], v[102:105]
	v_mfma_f32_16x16x32_bf16 v[98:101], v[194:197], v[218:221], v[98:101]
	v_mfma_f32_16x16x32_bf16 v[98:101], v[198:201], v[222:225], v[98:101]
	v_mfma_f32_16x16x32_bf16 v[70:73], v[186:189], v[226:229], v[70:73]
	v_mfma_f32_16x16x32_bf16 v[70:73], v[190:193], v[230:233], v[70:73]
	v_mfma_f32_16x16x32_bf16 v[66:69], v[194:197], v[226:229], v[66:69]
	v_mfma_f32_16x16x32_bf16 v[66:69], v[198:201], v[230:233], v[66:69]
	s_setprio 0
	s_barrier
; #define PG8_STAGE(bufoff, gbase, voff) do { _Pragma("unroll") for (int _i = 0; _i < 2; ++_i) \
;         __builtin_amdgcn_global_load_lds((const unsigned*)((const char*)(gbase) + (voff)[_i]), (PG8_LAS unsigned*)(lds + (bufoff) + ldsw + _i * 8192), 16, 0, 0); } while (0)
; #define PG8_LDA(dst, b, h) do { _Pragma("unroll") for (int m = 0; m < 4; ++m) _Pragma("unroll") for (int k = 0; k < 2; ++k) dst[m][k] = *(const PG8_LAS bf16x8*)(lds + PG8_SA(b, h) + aoff + m * 2048 + k * 1024); } while (0)
; #define PG8_MMA(ai, bj, At, Bt) do { __builtin_amdgcn_s_setprio(1); _Pragma("unroll") for (int m = 0; m < 4; ++m) _Pragma("unroll") for (int n = 0; n < 2; ++n) _Pragma("unroll") for (int k = 0; k < 2; ++k) \
;         acc[ai][bj][m][n] = __builtin_amdgcn_mfma_f32_16x16x32_bf16(Bt[n][k], At[m][k], acc[ai][bj][m][n], 0, 0, 0); __builtin_amdgcn_s_setprio(0); } while (0)
; #define PG8_WAIT_V(n) asm volatile("s_waitcnt vmcnt(" #n ")" ::: "memory")
; #define PG8_WAIT_L(n) asm volatile("s_waitcnt lgkmcnt(" #n ")" ::: "memory")
; #define PG8_BAR __builtin_amdgcn_s_barrier()
; #define PG8_SCHED __builtin_amdgcn_sched_barrier(0)
; template <class Epi, class Sched, bool ALIGN_EPI = false, bool SP2 = false>
; __device__ __forceinline__ void gemm_phase(PG8_LAS unsigned char* lds, const Gemm g, const Sched& S, const Epi& E) {
;     ...
;             PG8_LDA(At, 1, 1); PG8_STAGE(PG8_SB(1, 0), b3, voffB); PG8_STAGE(PG8_SB(1, 1), b3 + hstepB, voffB); PG8_STAGE(PG8_SA(1, 0), a3, voffA);
;             PG8_WAIT_V(8); PG8_WAIT_L(0); PG8_BAR; PG8_MMA(1, 0, At, B0); PG8_MMA(1, 1, At, B1); PG8_BAR; PG8_SCHED;
	s_add_i32 s34, s52, s37
	v_lshl_add_u64 v[234:235], v[234:235], 0, s[16:17]
	s_mov_b32 m0, s34
	ds_read_b128 v[202:205], v180 offset:49152
	ds_read_b128 v[206:209], v180 offset:50176
	ds_read_b128 v[210:213], v180 offset:51200
	ds_read_b128 v[214:217], v180 offset:52224
	ds_read_b128 v[218:221], v180 offset:53248
	ds_read_b128 v[222:225], v180 offset:54272
	ds_read_b128 v[226:229], v180 offset:55296
	ds_read_b128 v[230:233], v180 offset:56320
	global_load_lds_dwordx4 v[234:235], off
	s_add_i32 m0, s34, 0x2000
	s_add_u32 s10, s10, 0x40080
	v_lshl_add_u64 v[234:235], v[236:237], 0, s[16:17]
	s_addc_u32 s11, s11, 0
	s_add_i32 s34, s53, s37
	global_load_lds_dwordx4 v[234:235], off
	v_lshl_add_u64 v[234:235], s[10:11], 0, v[148:149]
	s_mov_b32 m0, s34
	s_nop 0
	global_load_lds_dwordx4 v[234:235], off
	v_lshl_add_u64 v[234:235], s[10:11], 0, v[152:153]
	s_add_i32 m0, s34, 0x2000
	s_nop 0
	global_load_lds_dwordx4 v[234:235], off
	v_lshl_add_u64 v[234:235], v[238:239], 0, s[16:17]
	s_mov_b32 m0, s40
	s_nop 0
	global_load_lds_dwordx4 v[234:235], off
	v_lshl_add_u64 v[234:235], v[240:241], 0, s[16:17]
	s_mov_b32 m0, s41
	s_nop 0
	global_load_lds_dwordx4 v[234:235], off
	s_waitcnt vmcnt(8)
	s_waitcnt lgkmcnt(0)
	s_barrier
	s_setprio 1
	s_waitcnt lgkmcnt(0)
	v_mfma_f32_16x16x32_bf16 v[62:65], v[82:85], v[202:205], v[62:65]
	v_mfma_f32_16x16x32_bf16 v[62:65], v[86:89], v[206:209], v[62:65]
	v_mfma_f32_16x16x32_bf16 v[58:61], v[90:93], v[202:205], v[58:61]
	v_mfma_f32_16x16x32_bf16 v[58:61], v[94:97], v[206:209], v[58:61]
	v_mfma_f32_16x16x32_bf16 v[46:49], v[82:85], v[210:213], v[46:49]
	v_mfma_f32_16x16x32_bf16 v[46:49], v[86:89], v[214:217], v[46:49]
	v_mfma_f32_16x16x32_bf16 v[42:45], v[90:93], v[210:213], v[42:45]
	v_mfma_f32_16x16x32_bf16 v[42:45], v[94:97], v[214:217], v[42:45]
	v_mfma_f32_16x16x32_bf16 v[30:33], v[82:85], v[218:221], v[30:33]
	v_mfma_f32_16x16x32_bf16 v[30:33], v[86:89], v[222:225], v[30:33]
	v_mfma_f32_16x16x32_bf16 v[26:29], v[90:93], v[218:221], v[26:29]
	v_mfma_f32_16x16x32_bf16 v[26:29], v[94:97], v[222:225], v[26:29]
	v_mfma_f32_16x16x32_bf16 v[14:17], v[82:85], v[226:229], v[14:17]
	v_mfma_f32_16x16x32_bf16 v[14:17], v[86:89], v[230:233], v[14:17]
	v_mfma_f32_16x16x32_bf16 v[10:13], v[90:93], v[226:229], v[10:13]
	v_mfma_f32_16x16x32_bf16 v[10:13], v[94:97], v[230:233], v[10:13]
	s_setprio 0
	s_setprio 1
	v_mfma_f32_16x16x32_bf16 v[54:57], v[186:189], v[202:205], v[54:57]
	v_mfma_f32_16x16x32_bf16 v[54:57], v[190:193], v[206:209], v[54:57]
	v_mfma_f32_16x16x32_bf16 v[50:53], v[194:197], v[202:205], v[50:53]
	v_mfma_f32_16x16x32_bf16 v[50:53], v[198:201], v[206:209], v[50:53]
	v_mfma_f32_16x16x32_bf16 v[38:41], v[186:189], v[210:213], v[38:41]
	v_mfma_f32_16x16x32_bf16 v[38:41], v[190:193], v[214:217], v[38:41]
	v_mfma_f32_16x16x32_bf16 v[34:37], v[194:197], v[210:213], v[34:37]
	v_mfma_f32_16x16x32_bf16 v[34:37], v[198:201], v[214:217], v[34:37]
	v_mfma_f32_16x16x32_bf16 v[22:25], v[186:189], v[218:221], v[22:25]
	v_mfma_f32_16x16x32_bf16 v[22:25], v[190:193], v[222:225], v[22:25]
	v_mfma_f32_16x16x32_bf16 v[18:21], v[194:197], v[218:221], v[18:21]
	v_mfma_f32_16x16x32_bf16 v[18:21], v[198:201], v[222:225], v[18:21]
	v_mfma_f32_16x16x32_bf16 v[6:9], v[186:189], v[226:229], v[6:9]
	v_mfma_f32_16x16x32_bf16 v[6:9], v[190:193], v[230:233], v[6:9]
	v_mfma_f32_16x16x32_bf16 v[2:5], v[194:197], v[226:229], v[2:5]
	v_mfma_f32_16x16x32_bf16 v[2:5], v[198:201], v[230:233], v[2:5]
	s_setprio 0
	s_barrier
	s_add_i32 s51, s51, 2
	s_add_u32 s6, s6, 0x100
	s_addc_u32 s7, s7, 0
	s_add_u32 s49, s49, 0x100
	s_addc_u32 s50, s50, 0
	s_cmp_gt_u32 s51, 61
	s_cbranch_scc0 .LBB0_402
	s_and_b64 vcc, exec, s[18:19]
	s_cbranch_vccz .LBB0_405
	s_barrier

; #define PG8_STAGE(bufoff, gbase, voff) do { _Pragma("unroll") for (int _i = 0; _i < 2; ++_i) \
;         __builtin_amdgcn_global_load_lds((const unsigned*)((const char*)(gbase) + (voff)[_i]), (PG8_LAS unsigned*)(lds + (bufoff) + ldsw + _i * 8192), 16, 0, 0); } while (0)
; #define PG8_LDA(dst, b, h) do { _Pragma("unroll") for (int m = 0; m < 4; ++m) _Pragma("unroll") for (int k = 0; k < 2; ++k) dst[m][k] = *(const PG8_LAS bf16x8*)(lds + PG8_SA(b, h) + aoff + m * 2048 + k * 1024); } while (0)
; #define PG8_LDB(dst, b, h) do { _Pragma("unroll") for (int n = 0; n < 2; ++n) _Pragma("unroll") for (int k = 0; k < 2; ++k) dst[n][k] = *(const PG8_LAS bf16x8*)(lds + PG8_SB(b, h) + boff + n * 2048 + k * 1024); } while (0)
; #define PG8_MMA(ai, bj, At, Bt) do { __builtin_amdgcn_s_setprio(1); _Pragma("unroll") for (int m = 0; m < 4; ++m) _Pragma("unroll") for (int n = 0; n < 2; ++n) _Pragma("unroll") for (int k = 0; k < 2; ++k) \
;         acc[ai][bj][m][n] = __builtin_amdgcn_mfma_f32_16x16x32_bf16(Bt[n][k], At[m][k], acc[ai][bj][m][n], 0, 0, 0); __builtin_amdgcn_s_setprio(0); } while (0)
; #define PG8_WAIT_V(n) asm volatile("s_waitcnt vmcnt(" #n ")" ::: "memory")
; #define PG8_WAIT_L(n) asm volatile("s_waitcnt lgkmcnt(" #n ")" ::: "memory")
; #define PG8_BAR __builtin_amdgcn_s_barrier()
; #define PG8_SCHED __builtin_amdgcn_sched_barrier(0)
; template <class Epi, class Sched, bool ALIGN_EPI = false, bool SP2 = false>
; __device__ __forceinline__ void gemm_phase(PG8_LAS unsigned char* lds, const Gemm g, const Sched& S, const Epi& E) {
;     ...
;             PG8_LDB(B0, 0, 0); PG8_LDB(B1, 0, 1); PG8_SCHED; PG8_LDA(At, 0, 0); PG8_STAGE(PG8_SA(1, 1), a1 + hstep, voffA);
;             PG8_WAIT_V(8); PG8_WAIT_L(0); PG8_BAR; PG8_MMA(0, 0, At, B0); PG8_MMA(0, 1, At, B1); PG8_BAR; PG8_SCHED;
;             PG8_LDA(At, 0, 1); PG8_STAGE(PG8_SB(0, 0), b2, voffB); PG8_STAGE(PG8_SB(0, 1), b2 + hstepB, voffB); PG8_STAGE(PG8_SA(0, 0), a2, voffA);
;             PG8_WAIT_V(8); PG8_WAIT_L(0); PG8_BAR; PG8_MMA(1, 0, At, B0); PG8_MMA(1, 1, At, B1); PG8_BAR; PG8_SCHED;
.LBB0_1759:
	ds_read_b128 v[66:69], v168
	ds_read_b128 v[70:73], v168 offset:1024
	ds_read_b128 v[74:77], v168 offset:2048
	ds_read_b128 v[78:81], v168 offset:3072
	ds_read_b128 v[162:165], v169
	ds_read_b128 v[172:175], v169 offset:1024
	ds_read_b128 v[176:179], v169 offset:2048
	ds_read_b128 v[180:183], v169 offset:3072
	s_add_u32 s34, s30, 0xfff00080
	s_addc_u32 s35, s31, -1
	s_cmp_eq_u32 s63, 60
	s_cselect_b32 s37, s23, s35
	s_cselect_b32 s36, s59, s34
	s_cselect_b32 s35, s21, s62
	s_cselect_b32 s34, s60, s61
	v_lshl_add_u64 v[216:217], s[30:31], 0, v[154:155]
	s_add_i32 m0, s40, 0xc000
	ds_read_b128 v[184:187], v170
	ds_read_b128 v[188:191], v170 offset:1024
	ds_read_b128 v[192:195], v170 offset:2048
	ds_read_b128 v[196:199], v170 offset:3072
	ds_read_b128 v[200:203], v170 offset:4096
	ds_read_b128 v[204:207], v170 offset:5120
	ds_read_b128 v[208:211], v170 offset:6144
	ds_read_b128 v[212:215], v170 offset:7168
	global_load_lds_dwordx4 v[216:217], off
	v_lshl_add_u64 v[216:217], s[30:31], 0, v[156:157]
	s_add_i32 m0, s40, 0xe000
	s_nop 0
	global_load_lds_dwordx4 v[216:217], off
	s_waitcnt vmcnt(8)
	s_waitcnt lgkmcnt(0)
	s_barrier
	s_setprio 1
	s_waitcnt lgkmcnt(0)
	v_mfma_f32_16x16x32_bf16 v[142:145], v[66:69], v[184:187], v[142:145]
	v_mfma_f32_16x16x32_bf16 v[142:145], v[70:73], v[188:191], v[142:145]
	v_mfma_f32_16x16x32_bf16 v[138:141], v[74:77], v[184:187], v[138:141]
	v_mfma_f32_16x16x32_bf16 v[138:141], v[78:81], v[188:191], v[138:141]
	v_mfma_f32_16x16x32_bf16 v[126:129], v[66:69], v[192:195], v[126:129]
	v_mfma_f32_16x16x32_bf16 v[126:129], v[70:73], v[196:199], v[126:129]
	v_mfma_f32_16x16x32_bf16 v[122:125], v[74:77], v[192:195], v[122:125]
	v_mfma_f32_16x16x32_bf16 v[122:125], v[78:81], v[196:199], v[122:125]
	v_mfma_f32_16x16x32_bf16 v[110:113], v[66:69], v[200:203], v[110:113]
	v_mfma_f32_16x16x32_bf16 v[110:113], v[70:73], v[204:207], v[110:113]
	v_mfma_f32_16x16x32_bf16 v[106:109], v[74:77], v[200:203], v[106:109]
	v_mfma_f32_16x16x32_bf16 v[106:109], v[78:81], v[204:207], v[106:109]
	v_mfma_f32_16x16x32_bf16 v[94:97], v[66:69], v[208:211], v[94:97]
	v_mfma_f32_16x16x32_bf16 v[94:97], v[70:73], v[212:215], v[94:97]
	v_mfma_f32_16x16x32_bf16 v[90:93], v[74:77], v[208:211], v[90:93]
	v_mfma_f32_16x16x32_bf16 v[90:93], v[78:81], v[212:215], v[90:93]
	s_setprio 0
	s_setprio 1
	v_mfma_f32_16x16x32_bf16 v[134:137], v[162:165], v[184:187], v[134:137]
	v_mfma_f32_16x16x32_bf16 v[134:137], v[172:175], v[188:191], v[134:137]
	v_mfma_f32_16x16x32_bf16 v[130:133], v[176:179], v[184:187], v[130:133]
	v_mfma_f32_16x16x32_bf16 v[130:133], v[180:183], v[188:191], v[130:133]
	v_mfma_f32_16x16x32_bf16 v[118:121], v[162:165], v[192:195], v[118:121]
	v_mfma_f32_16x16x32_bf16 v[118:121], v[172:175], v[196:199], v[118:121]
	v_mfma_f32_16x16x32_bf16 v[114:117], v[176:179], v[192:195], v[114:117]
	v_mfma_f32_16x16x32_bf16 v[114:117], v[180:183], v[196:199], v[114:117]
	v_mfma_f32_16x16x32_bf16 v[102:105], v[162:165], v[200:203], v[102:105]
	v_mfma_f32_16x16x32_bf16 v[102:105], v[172:175], v[204:207], v[102:105]
	v_mfma_f32_16x16x32_bf16 v[98:101], v[176:179], v[200:203], v[98:101]
	v_mfma_f32_16x16x32_bf16 v[98:101], v[180:183], v[204:207], v[98:101]
	v_mfma_f32_16x16x32_bf16 v[86:89], v[162:165], v[208:211], v[86:89]
	v_mfma_f32_16x16x32_bf16 v[86:89], v[172:175], v[212:215], v[86:89]
	v_mfma_f32_16x16x32_bf16 v[82:85], v[176:179], v[208:211], v[82:85]
	v_mfma_f32_16x16x32_bf16 v[82:85], v[180:183], v[212:215], v[82:85]
	s_setprio 0
	s_barrier
	s_add_i32 s64, s50, s39
	v_lshl_add_u64 v[216:217], s[34:35], 0, v[148:149]
	s_mov_b32 m0, s64
	ds_read_b128 v[184:187], v170 offset:16384
	ds_read_b128 v[188:191], v170 offset:17408
	ds_read_b128 v[192:195], v170 offset:18432
	ds_read_b128 v[196:199], v170 offset:19456
	ds_read_b128 v[200:203], v170 offset:20480
	ds_read_b128 v[204:207], v170 offset:21504
	ds_read_b128 v[208:211], v170 offset:22528
	ds_read_b128 v[212:215], v170 offset:23552
	global_load_lds_dwordx4 v[216:217], off
	s_add_i32 m0, s64, 0x2000
	s_add_u32 s64, s34, 0x100000
	v_lshl_add_u64 v[218:219], s[34:35], 0, v[152:153]
	s_addc_u32 s65, s35, 0
	s_add_i32 s66, s51, s39
	global_load_lds_dwordx4 v[218:219], off
	v_lshl_add_u64 v[220:221], s[64:65], 0, v[148:149]
	s_mov_b32 m0, s66
	v_lshl_add_u64 v[222:223], s[36:37], 0, v[150:151]
	global_load_lds_dwordx4 v[220:221], off
	v_lshl_add_u64 v[220:221], s[64:65], 0, v[152:153]
	s_add_i32 m0, s66, 0x2000
	s_nop 0
	global_load_lds_dwordx4 v[220:221], off
	v_lshl_add_u64 v[220:221], s[36:37], 0, v[146:147]
	s_mov_b32 m0, s40
	s_nop 0
	global_load_lds_dwordx4 v[220:221], off
	s_mov_b32 m0, s41
	s_nop 0
	global_load_lds_dwordx4 v[222:223], off
	s_waitcnt vmcnt(8)
	s_waitcnt lgkmcnt(0)
	s_barrier
; #define PG8_STAGE(bufoff, gbase, voff) do { _Pragma("unroll") for (int _i = 0; _i < 2; ++_i) \
;         __builtin_amdgcn_global_load_lds((const unsigned*)((const char*)(gbase) + (voff)[_i]), (PG8_LAS unsigned*)(lds + (bufoff) + ldsw + _i * 8192), 16, 0, 0); } while (0)
; #define PG8_LDA(dst, b, h) do { _Pragma("unroll") for (int m = 0; m < 4; ++m) _Pragma("unroll") for (int k = 0; k < 2; ++k) dst[m][k] = *(const PG8_LAS bf16x8*)(lds + PG8_SA(b, h) + aoff + m * 2048 + k * 1024); } while (0)
; #define PG8_LDB(dst, b, h) do { _Pragma("unroll") for (int n = 0; n < 2; ++n) _Pragma("unroll") for (int k = 0; k < 2; ++k) dst[n][k] = *(const PG8_LAS bf16x8*)(lds + PG8_SB(b, h) + boff + n * 2048 + k * 1024); } while (0)
; #define PG8_MMA(ai, bj, At, Bt) do { __builtin_amdgcn_s_setprio(1); _Pragma("unroll") for (int m = 0; m < 4; ++m) _Pragma("unroll") for (int n = 0; n < 2; ++n) _Pragma("unroll") for (int k = 0; k < 2; ++k) \
;         acc[ai][bj][m][n] = __builtin_amdgcn_mfma_f32_16x16x32_bf16(Bt[n][k], At[m][k], acc[ai][bj][m][n], 0, 0, 0); __builtin_amdgcn_s_setprio(0); } while (0)
; #define PG8_WAIT_V(n) asm volatile("s_waitcnt vmcnt(" #n ")" ::: "memory")
; #define PG8_WAIT_L(n) asm volatile("s_waitcnt lgkmcnt(" #n ")" ::: "memory")
; #define PG8_BAR __builtin_amdgcn_s_barrier()
; #define PG8_SCHED __builtin_amdgcn_sched_barrier(0)
; template <class Epi, class Sched, bool ALIGN_EPI = false, bool SP2 = false>
; __device__ __forceinline__ void gemm_phase(PG8_LAS unsigned char* lds, const Gemm g, const Sched& S, const Epi& E) {
;     ...
;             PG8_WAIT_V(8); PG8_WAIT_L(0); PG8_BAR; PG8_MMA(1, 0, At, B0); PG8_MMA(1, 1, At, B1); PG8_BAR; PG8_SCHED;
;             PG8_LDB(B0, 1, 0); PG8_LDB(B1, 1, 1); PG8_SCHED; PG8_LDA(At, 1, 0); PG8_STAGE(PG8_SA(0, 1), a2 + hstep, voffA);
;             PG8_WAIT_V(8); PG8_WAIT_L(0); PG8_BAR; PG8_MMA(0, 0, At, B0); PG8_MMA(0, 1, At, B1); PG8_BAR; PG8_SCHED;
	s_setprio 1
	s_waitcnt lgkmcnt(0)
	v_mfma_f32_16x16x32_bf16 v[62:65], v[66:69], v[184:187], v[62:65]
	v_mfma_f32_16x16x32_bf16 v[62:65], v[70:73], v[188:191], v[62:65]
	v_mfma_f32_16x16x32_bf16 v[58:61], v[74:77], v[184:187], v[58:61]
	v_mfma_f32_16x16x32_bf16 v[58:61], v[78:81], v[188:191], v[58:61]
	v_mfma_f32_16x16x32_bf16 v[46:49], v[66:69], v[192:195], v[46:49]
	v_mfma_f32_16x16x32_bf16 v[46:49], v[70:73], v[196:199], v[46:49]
	v_mfma_f32_16x16x32_bf16 v[42:45], v[74:77], v[192:195], v[42:45]
	v_mfma_f32_16x16x32_bf16 v[42:45], v[78:81], v[196:199], v[42:45]
	v_mfma_f32_16x16x32_bf16 v[30:33], v[66:69], v[200:203], v[30:33]
	v_mfma_f32_16x16x32_bf16 v[30:33], v[70:73], v[204:207], v[30:33]
	v_mfma_f32_16x16x32_bf16 v[26:29], v[74:77], v[200:203], v[26:29]
	v_mfma_f32_16x16x32_bf16 v[26:29], v[78:81], v[204:207], v[26:29]
	v_mfma_f32_16x16x32_bf16 v[22:25], v[66:69], v[208:211], v[22:25]
	v_mfma_f32_16x16x32_bf16 v[22:25], v[70:73], v[212:215], v[22:25]
	v_mfma_f32_16x16x32_bf16 v[18:21], v[74:77], v[208:211], v[18:21]
	v_mfma_f32_16x16x32_bf16 v[18:21], v[78:81], v[212:215], v[18:21]
	s_setprio 0
	s_setprio 1
	v_mfma_f32_16x16x32_bf16 v[54:57], v[162:165], v[184:187], v[54:57]
	v_mfma_f32_16x16x32_bf16 v[54:57], v[172:175], v[188:191], v[54:57]
	v_mfma_f32_16x16x32_bf16 v[50:53], v[176:179], v[184:187], v[50:53]
	v_mfma_f32_16x16x32_bf16 v[50:53], v[180:183], v[188:191], v[50:53]
	v_mfma_f32_16x16x32_bf16 v[38:41], v[162:165], v[192:195], v[38:41]
	v_mfma_f32_16x16x32_bf16 v[38:41], v[172:175], v[196:199], v[38:41]
	v_mfma_f32_16x16x32_bf16 v[34:37], v[176:179], v[192:195], v[34:37]
	v_mfma_f32_16x16x32_bf16 v[34:37], v[180:183], v[196:199], v[34:37]
	v_mfma_f32_16x16x32_bf16 v[14:17], v[162:165], v[200:203], v[14:17]
	v_mfma_f32_16x16x32_bf16 v[14:17], v[172:175], v[204:207], v[14:17]
	v_mfma_f32_16x16x32_bf16 v[10:13], v[176:179], v[200:203], v[10:13]
	v_mfma_f32_16x16x32_bf16 v[10:13], v[180:183], v[204:207], v[10:13]
	v_mfma_f32_16x16x32_bf16 v[6:9], v[162:165], v[208:211], v[6:9]
	v_mfma_f32_16x16x32_bf16 v[6:9], v[172:175], v[212:215], v[6:9]
	v_mfma_f32_16x16x32_bf16 v[2:5], v[176:179], v[208:211], v[2:5]
	v_mfma_f32_16x16x32_bf16 v[2:5], v[180:183], v[212:215], v[2:5]
	s_setprio 0
	s_barrier
	s_add_i32 s64, 0, 0x18000
	s_add_i32 s65, 0, 0x1c000
	v_add_u32_e32 v78, s64, v166
	v_add_u32_e32 v171, s65, v166
	ds_read_b128 v[66:69], v78
	ds_read_b128 v[70:73], v78 offset:1024
	ds_read_b128 v[74:77], v78 offset:2048
	ds_read_b128 v[78:81], v78 offset:3072
	ds_read_b128 v[162:165], v171
	ds_read_b128 v[172:175], v171 offset:1024
	ds_read_b128 v[176:179], v171 offset:2048
	ds_read_b128 v[180:183], v171 offset:3072
	s_add_u32 s36, s36, 0x100000
	s_addc_u32 s37, s37, 0
	s_mov_b32 m0, s42
	v_lshl_add_u64 v[224:225], s[36:37], 0, v[146:147]
	ds_read_b128 v[184:187], v170 offset:32768
	ds_read_b128 v[188:191], v170 offset:33792
	ds_read_b128 v[192:195], v170 offset:34816
	ds_read_b128 v[196:199], v170 offset:35840
	ds_read_b128 v[200:203], v170 offset:36864
	ds_read_b128 v[204:207], v170 offset:37888
	ds_read_b128 v[208:211], v170 offset:38912
	ds_read_b128 v[212:215], v170 offset:39936
	global_load_lds_dwordx4 v[224:225], off
	v_lshl_add_u64 v[224:225], s[36:37], 0, v[150:151]
	s_mov_b32 m0, s43
	s_nop 0
	global_load_lds_dwordx4 v[224:225], off
	s_waitcnt vmcnt(8)
	s_waitcnt lgkmcnt(0)
	s_barrier
	s_setprio 1
	s_waitcnt lgkmcnt(0)
	v_mfma_f32_16x16x32_bf16 v[142:145], v[66:69], v[184:187], v[142:145]
	v_mfma_f32_16x16x32_bf16 v[142:145], v[70:73], v[188:191], v[142:145]
	v_mfma_f32_16x16x32_bf16 v[138:141], v[74:77], v[184:187], v[138:141]
	v_mfma_f32_16x16x32_bf16 v[138:141], v[78:81], v[188:191], v[138:141]
	v_mfma_f32_16x16x32_bf16 v[126:129], v[66:69], v[192:195], v[126:129]
	v_mfma_f32_16x16x32_bf16 v[126:129], v[70:73], v[196:199], v[126:129]
	v_mfma_f32_16x16x32_bf16 v[122:125], v[74:77], v[192:195], v[122:125]
	v_mfma_f32_16x16x32_bf16 v[122:125], v[78:81], v[196:199], v[122:125]
	v_mfma_f32_16x16x32_bf16 v[110:113], v[66:69], v[200:203], v[110:113]
	v_mfma_f32_16x16x32_bf16 v[110:113], v[70:73], v[204:207], v[110:113]
	v_mfma_f32_16x16x32_bf16 v[106:109], v[74:77], v[200:203], v[106:109]
	v_mfma_f32_16x16x32_bf16 v[106:109], v[78:81], v[204:207], v[106:109]
	v_mfma_f32_16x16x32_bf16 v[94:97], v[66:69], v[208:211], v[94:97]
	v_mfma_f32_16x16x32_bf16 v[94:97], v[70:73], v[212:215], v[94:97]
	v_mfma_f32_16x16x32_bf16 v[90:93], v[74:77], v[208:211], v[90:93]
	v_mfma_f32_16x16x32_bf16 v[90:93], v[78:81], v[212:215], v[90:93]
	s_setprio 0
	s_setprio 1
	v_mfma_f32_16x16x32_bf16 v[134:137], v[162:165], v[184:187], v[134:137]
	v_mfma_f32_16x16x32_bf16 v[134:137], v[172:175], v[188:191], v[134:137]
	v_mfma_f32_16x16x32_bf16 v[130:133], v[176:179], v[184:187], v[130:133]
	v_mfma_f32_16x16x32_bf16 v[130:133], v[180:183], v[188:191], v[130:133]
	v_mfma_f32_16x16x32_bf16 v[118:121], v[162:165], v[192:195], v[118:121]
	v_mfma_f32_16x16x32_bf16 v[118:121], v[172:175], v[196:199], v[118:121]
	v_mfma_f32_16x16x32_bf16 v[114:117], v[176:179], v[192:195], v[114:117]
	v_mfma_f32_16x16x32_bf16 v[114:117], v[180:183], v[196:199], v[114:117]
	v_mfma_f32_16x16x32_bf16 v[102:105], v[162:165], v[200:203], v[102:105]
	v_mfma_f32_16x16x32_bf16 v[102:105], v[172:175], v[204:207], v[102:105]
	v_mfma_f32_16x16x32_bf16 v[98:101], v[176:179], v[200:203], v[98:101]
	v_mfma_f32_16x16x32_bf16 v[98:101], v[180:183], v[204:207], v[98:101]
	v_mfma_f32_16x16x32_bf16 v[86:89], v[162:165], v[208:211], v[86:89]
	v_mfma_f32_16x16x32_bf16 v[86:89], v[172:175], v[212:215], v[86:89]
	v_mfma_f32_16x16x32_bf16 v[82:85], v[176:179], v[208:211], v[82:85]
	v_mfma_f32_16x16x32_bf16 v[82:85], v[180:183], v[212:215], v[82:85]
	s_setprio 0
	s_barrier
; #define PG8_STAGE(bufoff, gbase, voff) do { _Pragma("unroll") for (int _i = 0; _i < 2; ++_i) \
;         __builtin_amdgcn_global_load_lds((const unsigned*)((const char*)(gbase) + (voff)[_i]), (PG8_LAS unsigned*)(lds + (bufoff) + ldsw + _i * 8192), 16, 0, 0); } while (0)
; #define PG8_LDA(dst, b, h) do { _Pragma("unroll") for (int m = 0; m < 4; ++m) _Pragma("unroll") for (int k = 0; k < 2; ++k) dst[m][k] = *(const PG8_LAS bf16x8*)(lds + PG8_SA(b, h) + aoff + m * 2048 + k * 1024); } while (0)
; #define PG8_MMA(ai, bj, At, Bt) do { __builtin_amdgcn_s_setprio(1); _Pragma("unroll") for (int m = 0; m < 4; ++m) _Pragma("unroll") for (int n = 0; n < 2; ++n) _Pragma("unroll") for (int k = 0; k < 2; ++k) \
;         acc[ai][bj][m][n] = __builtin_amdgcn_mfma_f32_16x16x32_bf16(Bt[n][k], At[m][k], acc[ai][bj][m][n], 0, 0, 0); __builtin_amdgcn_s_setprio(0); } while (0)
; #define PG8_WAIT_V(n) asm volatile("s_waitcnt vmcnt(" #n ")" ::: "memory")
; #define PG8_WAIT_L(n) asm volatile("s_waitcnt lgkmcnt(" #n ")" ::: "memory")
; #define PG8_BAR __builtin_amdgcn_s_barrier()
; #define PG8_SCHED __builtin_amdgcn_sched_barrier(0)
; template <class Epi, class Sched, bool ALIGN_EPI = false, bool SP2 = false>
; __device__ __forceinline__ void gemm_phase(PG8_LAS unsigned char* lds, const Gemm g, const Sched& S, const Epi& E) {
;     ...
;             PG8_LDA(At, 1, 1); PG8_STAGE(PG8_SB(1, 0), b3, voffB); PG8_STAGE(PG8_SB(1, 1), b3 + hstepB, voffB); PG8_STAGE(PG8_SA(1, 0), a3, voffA);
;             PG8_WAIT_V(8); PG8_WAIT_L(0); PG8_BAR; PG8_MMA(1, 0, At, B0); PG8_MMA(1, 1, At, B1); PG8_BAR; PG8_SCHED;
	s_add_i32 s36, s64, s39
	v_lshl_add_u64 v[216:217], v[216:217], 0, s[6:7]
	s_mov_b32 m0, s36
	ds_read_b128 v[184:187], v170 offset:49152
	ds_read_b128 v[188:191], v170 offset:50176
	ds_read_b128 v[192:195], v170 offset:51200
	ds_read_b128 v[196:199], v170 offset:52224
	ds_read_b128 v[200:203], v170 offset:53248
	ds_read_b128 v[204:207], v170 offset:54272
	ds_read_b128 v[208:211], v170 offset:55296
	ds_read_b128 v[212:215], v170 offset:56320
	global_load_lds_dwordx4 v[216:217], off
	s_add_i32 m0, s36, 0x2000
	s_add_u32 s34, s34, 0x100080
	v_lshl_add_u64 v[216:217], v[218:219], 0, s[6:7]
	s_addc_u32 s35, s35, 0
	s_add_i32 s36, s65, s39
	global_load_lds_dwordx4 v[216:217], off
	v_lshl_add_u64 v[216:217], s[34:35], 0, v[148:149]
	s_mov_b32 m0, s36
	s_nop 0
	global_load_lds_dwordx4 v[216:217], off
	v_lshl_add_u64 v[216:217], s[34:35], 0, v[152:153]
	s_add_i32 m0, s36, 0x2000
	s_nop 0
	global_load_lds_dwordx4 v[216:217], off
	v_lshl_add_u64 v[216:217], v[220:221], 0, s[6:7]
	s_mov_b32 m0, s47
	s_nop 0
	global_load_lds_dwordx4 v[216:217], off
	v_lshl_add_u64 v[216:217], v[222:223], 0, s[6:7]
	s_mov_b32 m0, s48
	s_nop 0
	global_load_lds_dwordx4 v[216:217], off
	s_waitcnt vmcnt(8)
	s_waitcnt lgkmcnt(0)
	s_barrier
	s_setprio 1
	s_waitcnt lgkmcnt(0)
	v_mfma_f32_16x16x32_bf16 v[62:65], v[66:69], v[184:187], v[62:65]
	v_mfma_f32_16x16x32_bf16 v[62:65], v[70:73], v[188:191], v[62:65]
	v_mfma_f32_16x16x32_bf16 v[58:61], v[74:77], v[184:187], v[58:61]
	v_mfma_f32_16x16x32_bf16 v[58:61], v[78:81], v[188:191], v[58:61]
	v_mfma_f32_16x16x32_bf16 v[46:49], v[66:69], v[192:195], v[46:49]
	v_mfma_f32_16x16x32_bf16 v[46:49], v[70:73], v[196:199], v[46:49]
	v_mfma_f32_16x16x32_bf16 v[42:45], v[74:77], v[192:195], v[42:45]
	v_mfma_f32_16x16x32_bf16 v[42:45], v[78:81], v[196:199], v[42:45]
	v_mfma_f32_16x16x32_bf16 v[30:33], v[66:69], v[200:203], v[30:33]
	v_mfma_f32_16x16x32_bf16 v[30:33], v[70:73], v[204:207], v[30:33]
	v_mfma_f32_16x16x32_bf16 v[26:29], v[74:77], v[200:203], v[26:29]
	v_mfma_f32_16x16x32_bf16 v[26:29], v[78:81], v[204:207], v[26:29]
	v_mfma_f32_16x16x32_bf16 v[22:25], v[66:69], v[208:211], v[22:25]
	v_mfma_f32_16x16x32_bf16 v[22:25], v[70:73], v[212:215], v[22:25]
	v_mfma_f32_16x16x32_bf16 v[18:21], v[74:77], v[208:211], v[18:21]
	v_mfma_f32_16x16x32_bf16 v[18:21], v[78:81], v[212:215], v[18:21]
	s_setprio 0
	s_setprio 1
	v_mfma_f32_16x16x32_bf16 v[54:57], v[162:165], v[184:187], v[54:57]
	v_mfma_f32_16x16x32_bf16 v[54:57], v[172:175], v[188:191], v[54:57]
	v_mfma_f32_16x16x32_bf16 v[50:53], v[176:179], v[184:187], v[50:53]
	v_mfma_f32_16x16x32_bf16 v[50:53], v[180:183], v[188:191], v[50:53]
	v_mfma_f32_16x16x32_bf16 v[38:41], v[162:165], v[192:195], v[38:41]
	v_mfma_f32_16x16x32_bf16 v[38:41], v[172:175], v[196:199], v[38:41]
	v_mfma_f32_16x16x32_bf16 v[34:37], v[176:179], v[192:195], v[34:37]
	v_mfma_f32_16x16x32_bf16 v[34:37], v[180:183], v[196:199], v[34:37]
	v_mfma_f32_16x16x32_bf16 v[14:17], v[162:165], v[200:203], v[14:17]
	v_mfma_f32_16x16x32_bf16 v[14:17], v[172:175], v[204:207], v[14:17]
	v_mfma_f32_16x16x32_bf16 v[10:13], v[176:179], v[200:203], v[10:13]
	v_mfma_f32_16x16x32_bf16 v[10:13], v[180:183], v[204:207], v[10:13]
	v_mfma_f32_16x16x32_bf16 v[6:9], v[162:165], v[208:211], v[6:9]
	v_mfma_f32_16x16x32_bf16 v[6:9], v[172:175], v[212:215], v[6:9]
	v_mfma_f32_16x16x32_bf16 v[2:5], v[176:179], v[208:211], v[2:5]
	v_mfma_f32_16x16x32_bf16 v[2:5], v[180:183], v[212:215], v[2:5]
	s_setprio 0
	s_barrier
	s_add_i32 s63, s63, 2
	s_add_u32 s30, s30, 0x100
	s_addc_u32 s31, s31, 0
	s_add_u32 s61, s61, 0x100
	s_addc_u32 s62, s62, 0
	s_cmp_gt_u32 s63, 61
	s_cbranch_scc0 .LBB0_1759
	s_and_b64 vcc, exec, s[8:9]
	s_cbranch_vccz .LBB0_1762
	s_barrier

; #define PG8_STAGE(bufoff, gbase, voff) do { _Pragma("unroll") for (int _i = 0; _i < 2; ++_i) \
;         __builtin_amdgcn_global_load_lds((const unsigned*)((const char*)(gbase) + (voff)[_i]), (PG8_LAS unsigned*)(lds + (bufoff) + ldsw + _i * 8192), 16, 0, 0); } while (0)
; #define PG8_LDA(dst, b, h) do { _Pragma("unroll") for (int m = 0; m < 4; ++m) _Pragma("unroll") for (int k = 0; k < 2; ++k) dst[m][k] = *(const PG8_LAS bf16x8*)(lds + PG8_SA(b, h) + aoff + m * 2048 + k * 1024); } while (0)
; #define PG8_LDB(dst, b, h) do { _Pragma("unroll") for (int n = 0; n < 2; ++n) _Pragma("unroll") for (int k = 0; k < 2; ++k) dst[n][k] = *(const PG8_LAS bf16x8*)(lds + PG8_SB(b, h) + boff + n * 2048 + k * 1024); } while (0)
; #define PG8_MMA(ai, bj, At, Bt) do { __builtin_amdgcn_s_setprio(1); _Pragma("unroll") for (int m = 0; m < 4; ++m) _Pragma("unroll") for (int n = 0; n < 2; ++n) _Pragma("unroll") for (int k = 0; k < 2; ++k) \
;         acc[ai][bj][m][n] = __builtin_amdgcn_mfma_f32_16x16x32_bf16(Bt[n][k], At[m][k], acc[ai][bj][m][n], 0, 0, 0); __builtin_amdgcn_s_setprio(0); } while (0)
; #define PG8_WAIT_V(n) asm volatile("s_waitcnt vmcnt(" #n ")" ::: "memory")
; #define PG8_WAIT_L(n) asm volatile("s_waitcnt lgkmcnt(" #n ")" ::: "memory")
; #define PG8_BAR __builtin_amdgcn_s_barrier()
; #define PG8_SCHED __builtin_amdgcn_sched_barrier(0)
; template <class Epi, class Sched, bool ALIGN_EPI = false, bool SP2 = false>
; __device__ __forceinline__ void gemm_phase(PG8_LAS unsigned char* lds, const Gemm g, const Sched& S, const Epi& E) {
;     ...
;             PG8_LDB(B0, 0, 0); PG8_LDB(B1, 0, 1); PG8_SCHED; PG8_LDA(At, 0, 0); PG8_STAGE(PG8_SA(1, 1), a1 + hstep, voffA);
;             PG8_WAIT_V(8); PG8_WAIT_L(0); PG8_BAR; PG8_MMA(0, 0, At, B0); PG8_MMA(0, 1, At, B1); PG8_BAR; PG8_SCHED;
;             PG8_LDA(At, 0, 1); PG8_STAGE(PG8_SB(0, 0), b2, voffB); PG8_STAGE(PG8_SB(0, 1), b2 + hstepB, voffB); PG8_STAGE(PG8_SA(0, 0), a2, voffA);
;             PG8_WAIT_V(8); PG8_WAIT_L(0); PG8_BAR; PG8_MMA(1, 0, At, B0); PG8_MMA(1, 1, At, B1); PG8_BAR; PG8_SCHED;
.LBB0_1889:
	ds_read_b128 v[146:149], v152
	ds_read_b128 v[156:159], v152 offset:1024
	ds_read_b128 v[160:163], v152 offset:2048
	ds_read_b128 v[164:167], v152 offset:3072
	ds_read_b128 v[168:171], v153
	ds_read_b128 v[172:175], v153 offset:1024
	ds_read_b128 v[176:179], v153 offset:2048
	ds_read_b128 v[180:183], v153 offset:3072
	s_add_u32 s16, s14, 0x100
	s_addc_u32 s17, s15, 0
	s_cmp_eq_u32 s44, 60
	s_cselect_b32 s21, s5, s17
	s_cselect_b32 s20, s4, s16
	s_cselect_b32 s19, s13, s43
	s_cselect_b32 s18, s12, s42
	v_lshl_add_u64 v[216:217], s[14:15], 0, v[138:139]
	s_add_i32 m0, s26, 0xc000
	ds_read_b128 v[184:187], v154
	ds_read_b128 v[188:191], v154 offset:1024
	ds_read_b128 v[192:195], v154 offset:2048
	ds_read_b128 v[196:199], v154 offset:3072
	ds_read_b128 v[200:203], v154 offset:4096
	ds_read_b128 v[204:207], v154 offset:5120
	ds_read_b128 v[208:211], v154 offset:6144
	ds_read_b128 v[212:215], v154 offset:7168
	global_load_lds_dwordx4 v[216:217], off
	v_lshl_add_u64 v[216:217], s[14:15], 0, v[140:141]
	s_add_i32 m0, s26, 0xe000
	s_nop 0
	global_load_lds_dwordx4 v[216:217], off
	s_waitcnt vmcnt(8)
	s_waitcnt lgkmcnt(0)
	s_barrier
	s_setprio 1
	s_waitcnt lgkmcnt(0)
	v_mfma_f32_16x16x32_bf16 v[126:129], v[146:149], v[184:187], v[126:129]
	v_mfma_f32_16x16x32_bf16 v[126:129], v[156:159], v[188:191], v[126:129]
	v_mfma_f32_16x16x32_bf16 v[122:125], v[160:163], v[184:187], v[122:125]
	v_mfma_f32_16x16x32_bf16 v[122:125], v[164:167], v[188:191], v[122:125]
	v_mfma_f32_16x16x32_bf16 v[110:113], v[146:149], v[192:195], v[110:113]
	v_mfma_f32_16x16x32_bf16 v[110:113], v[156:159], v[196:199], v[110:113]
	v_mfma_f32_16x16x32_bf16 v[106:109], v[160:163], v[192:195], v[106:109]
	v_mfma_f32_16x16x32_bf16 v[106:109], v[164:167], v[196:199], v[106:109]
	v_mfma_f32_16x16x32_bf16 v[94:97], v[146:149], v[200:203], v[94:97]
	v_mfma_f32_16x16x32_bf16 v[94:97], v[156:159], v[204:207], v[94:97]
	v_mfma_f32_16x16x32_bf16 v[90:93], v[160:163], v[200:203], v[90:93]
	v_mfma_f32_16x16x32_bf16 v[90:93], v[164:167], v[204:207], v[90:93]
	v_mfma_f32_16x16x32_bf16 v[78:81], v[146:149], v[208:211], v[78:81]
	v_mfma_f32_16x16x32_bf16 v[78:81], v[156:159], v[212:215], v[78:81]
	v_mfma_f32_16x16x32_bf16 v[74:77], v[160:163], v[208:211], v[74:77]
	v_mfma_f32_16x16x32_bf16 v[74:77], v[164:167], v[212:215], v[74:77]
	s_setprio 0
	s_setprio 1
	v_mfma_f32_16x16x32_bf16 v[118:121], v[168:171], v[184:187], v[118:121]
	v_mfma_f32_16x16x32_bf16 v[118:121], v[172:175], v[188:191], v[118:121]
	v_mfma_f32_16x16x32_bf16 v[114:117], v[176:179], v[184:187], v[114:117]
	v_mfma_f32_16x16x32_bf16 v[114:117], v[180:183], v[188:191], v[114:117]
	v_mfma_f32_16x16x32_bf16 v[102:105], v[168:171], v[192:195], v[102:105]
	v_mfma_f32_16x16x32_bf16 v[102:105], v[172:175], v[196:199], v[102:105]
	v_mfma_f32_16x16x32_bf16 v[98:101], v[176:179], v[192:195], v[98:101]
	v_mfma_f32_16x16x32_bf16 v[98:101], v[180:183], v[196:199], v[98:101]
	v_mfma_f32_16x16x32_bf16 v[86:89], v[168:171], v[200:203], v[86:89]
	v_mfma_f32_16x16x32_bf16 v[86:89], v[172:175], v[204:207], v[86:89]
	v_mfma_f32_16x16x32_bf16 v[82:85], v[176:179], v[200:203], v[82:85]
	v_mfma_f32_16x16x32_bf16 v[82:85], v[180:183], v[204:207], v[82:85]
	v_mfma_f32_16x16x32_bf16 v[70:73], v[168:171], v[208:211], v[70:73]
	v_mfma_f32_16x16x32_bf16 v[70:73], v[172:175], v[212:215], v[70:73]
	v_mfma_f32_16x16x32_bf16 v[66:69], v[176:179], v[208:211], v[66:69]
	v_mfma_f32_16x16x32_bf16 v[66:69], v[180:183], v[212:215], v[66:69]
	s_setprio 0
	s_barrier
	s_add_i32 s14, s35, s2
	v_lshl_add_u64 v[216:217], s[18:19], 0, v[134:135]
	s_mov_b32 m0, s14
	ds_read_b128 v[184:187], v154 offset:16384
	ds_read_b128 v[188:191], v154 offset:17408
	ds_read_b128 v[192:195], v154 offset:18432
	ds_read_b128 v[196:199], v154 offset:19456
	ds_read_b128 v[200:203], v154 offset:20480
	ds_read_b128 v[204:207], v154 offset:21504
	ds_read_b128 v[208:211], v154 offset:22528
	ds_read_b128 v[212:215], v154 offset:23552
	global_load_lds_dwordx4 v[216:217], off
	s_add_i32 m0, s14, 0x2000
	s_add_u32 s14, s18, 0x108000
	v_lshl_add_u64 v[218:219], s[18:19], 0, v[130:131]
	s_addc_u32 s15, s19, 0
	s_add_i32 s45, s36, s2
	global_load_lds_dwordx4 v[218:219], off
	v_lshl_add_u64 v[220:221], s[14:15], 0, v[134:135]
	s_mov_b32 m0, s45
	v_lshl_add_u64 v[222:223], s[20:21], 0, v[132:133]
	global_load_lds_dwordx4 v[220:221], off
	v_lshl_add_u64 v[220:221], s[14:15], 0, v[130:131]
	s_add_i32 m0, s45, 0x2000
	s_nop 0
	global_load_lds_dwordx4 v[220:221], off
	v_lshl_add_u64 v[220:221], s[20:21], 0, v[136:137]
	s_mov_b32 m0, s26
	s_nop 0
	global_load_lds_dwordx4 v[220:221], off
	s_mov_b32 m0, s27
	s_nop 0
	global_load_lds_dwordx4 v[222:223], off
	s_waitcnt vmcnt(8)
	s_waitcnt lgkmcnt(0)
	s_barrier
; #define PG8_STAGE(bufoff, gbase, voff) do { _Pragma("unroll") for (int _i = 0; _i < 2; ++_i) \
;         __builtin_amdgcn_global_load_lds((const unsigned*)((const char*)(gbase) + (voff)[_i]), (PG8_LAS unsigned*)(lds + (bufoff) + ldsw + _i * 8192), 16, 0, 0); } while (0)
; #define PG8_LDA(dst, b, h) do { _Pragma("unroll") for (int m = 0; m < 4; ++m) _Pragma("unroll") for (int k = 0; k < 2; ++k) dst[m][k] = *(const PG8_LAS bf16x8*)(lds + PG8_SA(b, h) + aoff + m * 2048 + k * 1024); } while (0)
; #define PG8_LDB(dst, b, h) do { _Pragma("unroll") for (int n = 0; n < 2; ++n) _Pragma("unroll") for (int k = 0; k < 2; ++k) dst[n][k] = *(const PG8_LAS bf16x8*)(lds + PG8_SB(b, h) + boff + n * 2048 + k * 1024); } while (0)
; #define PG8_MMA(ai, bj, At, Bt) do { __builtin_amdgcn_s_setprio(1); _Pragma("unroll") for (int m = 0; m < 4; ++m) _Pragma("unroll") for (int n = 0; n < 2; ++n) _Pragma("unroll") for (int k = 0; k < 2; ++k) \
;         acc[ai][bj][m][n] = __builtin_amdgcn_mfma_f32_16x16x32_bf16(Bt[n][k], At[m][k], acc[ai][bj][m][n], 0, 0, 0); __builtin_amdgcn_s_setprio(0); } while (0)
; #define PG8_WAIT_V(n) asm volatile("s_waitcnt vmcnt(" #n ")" ::: "memory")
; #define PG8_WAIT_L(n) asm volatile("s_waitcnt lgkmcnt(" #n ")" ::: "memory")
; #define PG8_BAR __builtin_amdgcn_s_barrier()
; #define PG8_SCHED __builtin_amdgcn_sched_barrier(0)
; template <class Epi, class Sched, bool ALIGN_EPI = false, bool SP2 = false>
; __device__ __forceinline__ void gemm_phase(PG8_LAS unsigned char* lds, const Gemm g, const Sched& S, const Epi& E) {
;     ...
;             PG8_WAIT_V(8); PG8_WAIT_L(0); PG8_BAR; PG8_MMA(1, 0, At, B0); PG8_MMA(1, 1, At, B1); PG8_BAR; PG8_SCHED;
;             PG8_LDB(B0, 1, 0); PG8_LDB(B1, 1, 1); PG8_SCHED; PG8_LDA(At, 1, 0); PG8_STAGE(PG8_SA(0, 1), a2 + hstep, voffA);
;             PG8_WAIT_V(8); PG8_WAIT_L(0); PG8_BAR; PG8_MMA(0, 0, At, B0); PG8_MMA(0, 1, At, B1); PG8_BAR; PG8_SCHED;
	s_setprio 1
	s_waitcnt lgkmcnt(0)
	v_mfma_f32_16x16x32_bf16 v[62:65], v[146:149], v[184:187], v[62:65]
	v_mfma_f32_16x16x32_bf16 v[62:65], v[156:159], v[188:191], v[62:65]
	v_mfma_f32_16x16x32_bf16 v[58:61], v[160:163], v[184:187], v[58:61]
	v_mfma_f32_16x16x32_bf16 v[58:61], v[164:167], v[188:191], v[58:61]
	v_mfma_f32_16x16x32_bf16 v[46:49], v[146:149], v[192:195], v[46:49]
	v_mfma_f32_16x16x32_bf16 v[46:49], v[156:159], v[196:199], v[46:49]
	v_mfma_f32_16x16x32_bf16 v[42:45], v[160:163], v[192:195], v[42:45]
	v_mfma_f32_16x16x32_bf16 v[42:45], v[164:167], v[196:199], v[42:45]
	v_mfma_f32_16x16x32_bf16 v[30:33], v[146:149], v[200:203], v[30:33]
	v_mfma_f32_16x16x32_bf16 v[30:33], v[156:159], v[204:207], v[30:33]
	v_mfma_f32_16x16x32_bf16 v[26:29], v[160:163], v[200:203], v[26:29]
	v_mfma_f32_16x16x32_bf16 v[26:29], v[164:167], v[204:207], v[26:29]
	v_mfma_f32_16x16x32_bf16 v[14:17], v[146:149], v[208:211], v[14:17]
	v_mfma_f32_16x16x32_bf16 v[14:17], v[156:159], v[212:215], v[14:17]
	v_mfma_f32_16x16x32_bf16 v[10:13], v[160:163], v[208:211], v[10:13]
	v_mfma_f32_16x16x32_bf16 v[10:13], v[164:167], v[212:215], v[10:13]
	s_setprio 0
	s_setprio 1
	v_mfma_f32_16x16x32_bf16 v[54:57], v[168:171], v[184:187], v[54:57]
	v_mfma_f32_16x16x32_bf16 v[54:57], v[172:175], v[188:191], v[54:57]
	v_mfma_f32_16x16x32_bf16 v[50:53], v[176:179], v[184:187], v[50:53]
	v_mfma_f32_16x16x32_bf16 v[50:53], v[180:183], v[188:191], v[50:53]
	v_mfma_f32_16x16x32_bf16 v[38:41], v[168:171], v[192:195], v[38:41]
	v_mfma_f32_16x16x32_bf16 v[38:41], v[172:175], v[196:199], v[38:41]
	v_mfma_f32_16x16x32_bf16 v[34:37], v[176:179], v[192:195], v[34:37]
	v_mfma_f32_16x16x32_bf16 v[34:37], v[180:183], v[196:199], v[34:37]
	v_mfma_f32_16x16x32_bf16 v[22:25], v[168:171], v[200:203], v[22:25]
	v_mfma_f32_16x16x32_bf16 v[22:25], v[172:175], v[204:207], v[22:25]
	v_mfma_f32_16x16x32_bf16 v[18:21], v[176:179], v[200:203], v[18:21]
	v_mfma_f32_16x16x32_bf16 v[18:21], v[180:183], v[204:207], v[18:21]
	v_mfma_f32_16x16x32_bf16 v[6:9], v[168:171], v[208:211], v[6:9]
	v_mfma_f32_16x16x32_bf16 v[6:9], v[172:175], v[212:215], v[6:9]
	v_mfma_f32_16x16x32_bf16 v[2:5], v[176:179], v[208:211], v[2:5]
	v_mfma_f32_16x16x32_bf16 v[2:5], v[180:183], v[212:215], v[2:5]
	s_setprio 0
	s_barrier
	s_add_i32 s45, 0, 0x18000
	v_add_u32_e32 v155, s45, v150
	s_add_i32 s46, 0, 0x1c000
	ds_read_b128 v[146:149], v155
	ds_read_b128 v[156:159], v155 offset:1024
	ds_read_b128 v[160:163], v155 offset:2048
	ds_read_b128 v[164:167], v155 offset:3072
	v_add_u32_e32 v155, s46, v150
	ds_read_b128 v[168:171], v155
	ds_read_b128 v[172:175], v155 offset:1024
	ds_read_b128 v[176:179], v155 offset:2048
	ds_read_b128 v[180:183], v155 offset:3072
	s_add_u32 s14, s20, 0x108000
	s_addc_u32 s15, s21, 0
	s_mov_b32 m0, s28
	v_lshl_add_u64 v[224:225], s[14:15], 0, v[136:137]
	ds_read_b128 v[184:187], v154 offset:32768
	ds_read_b128 v[188:191], v154 offset:33792
	ds_read_b128 v[192:195], v154 offset:34816
	ds_read_b128 v[196:199], v154 offset:35840
	ds_read_b128 v[200:203], v154 offset:36864
	ds_read_b128 v[204:207], v154 offset:37888
	ds_read_b128 v[208:211], v154 offset:38912
	ds_read_b128 v[212:215], v154 offset:39936
	global_load_lds_dwordx4 v[224:225], off
	v_lshl_add_u64 v[224:225], s[14:15], 0, v[132:133]
	s_mov_b32 m0, s29
	s_nop 0
	global_load_lds_dwordx4 v[224:225], off
	s_waitcnt vmcnt(8)
	s_waitcnt lgkmcnt(0)
	s_barrier
	s_setprio 1
	s_waitcnt lgkmcnt(0)
	v_mfma_f32_16x16x32_bf16 v[126:129], v[146:149], v[184:187], v[126:129]
	v_mfma_f32_16x16x32_bf16 v[126:129], v[156:159], v[188:191], v[126:129]
	v_mfma_f32_16x16x32_bf16 v[122:125], v[160:163], v[184:187], v[122:125]
	v_mfma_f32_16x16x32_bf16 v[122:125], v[164:167], v[188:191], v[122:125]
	v_mfma_f32_16x16x32_bf16 v[110:113], v[146:149], v[192:195], v[110:113]
	v_mfma_f32_16x16x32_bf16 v[110:113], v[156:159], v[196:199], v[110:113]
	v_mfma_f32_16x16x32_bf16 v[106:109], v[160:163], v[192:195], v[106:109]
	v_mfma_f32_16x16x32_bf16 v[106:109], v[164:167], v[196:199], v[106:109]
	v_mfma_f32_16x16x32_bf16 v[94:97], v[146:149], v[200:203], v[94:97]
	v_mfma_f32_16x16x32_bf16 v[94:97], v[156:159], v[204:207], v[94:97]
	v_mfma_f32_16x16x32_bf16 v[90:93], v[160:163], v[200:203], v[90:93]
	v_mfma_f32_16x16x32_bf16 v[90:93], v[164:167], v[204:207], v[90:93]
	v_mfma_f32_16x16x32_bf16 v[78:81], v[146:149], v[208:211], v[78:81]
	v_mfma_f32_16x16x32_bf16 v[78:81], v[156:159], v[212:215], v[78:81]
	v_mfma_f32_16x16x32_bf16 v[74:77], v[160:163], v[208:211], v[74:77]
	v_mfma_f32_16x16x32_bf16 v[74:77], v[164:167], v[212:215], v[74:77]
	s_setprio 0
	s_setprio 1
	v_mfma_f32_16x16x32_bf16 v[118:121], v[168:171], v[184:187], v[118:121]
	v_mfma_f32_16x16x32_bf16 v[118:121], v[172:175], v[188:191], v[118:121]
	v_mfma_f32_16x16x32_bf16 v[114:117], v[176:179], v[184:187], v[114:117]
	v_mfma_f32_16x16x32_bf16 v[114:117], v[180:183], v[188:191], v[114:117]
	v_mfma_f32_16x16x32_bf16 v[102:105], v[168:171], v[192:195], v[102:105]
	v_mfma_f32_16x16x32_bf16 v[102:105], v[172:175], v[196:199], v[102:105]
	v_mfma_f32_16x16x32_bf16 v[98:101], v[176:179], v[192:195], v[98:101]
	v_mfma_f32_16x16x32_bf16 v[98:101], v[180:183], v[196:199], v[98:101]
	v_mfma_f32_16x16x32_bf16 v[86:89], v[168:171], v[200:203], v[86:89]
	v_mfma_f32_16x16x32_bf16 v[86:89], v[172:175], v[204:207], v[86:89]
	v_mfma_f32_16x16x32_bf16 v[82:85], v[176:179], v[200:203], v[82:85]
	v_mfma_f32_16x16x32_bf16 v[82:85], v[180:183], v[204:207], v[82:85]
	v_mfma_f32_16x16x32_bf16 v[70:73], v[168:171], v[208:211], v[70:73]
	v_mfma_f32_16x16x32_bf16 v[70:73], v[172:175], v[212:215], v[70:73]
	v_mfma_f32_16x16x32_bf16 v[66:69], v[176:179], v[208:211], v[66:69]
	v_mfma_f32_16x16x32_bf16 v[66:69], v[180:183], v[212:215], v[66:69]
	s_setprio 0
	s_barrier
; #define PG8_STAGE(bufoff, gbase, voff) do { _Pragma("unroll") for (int _i = 0; _i < 2; ++_i) \
;         __builtin_amdgcn_global_load_lds((const unsigned*)((const char*)(gbase) + (voff)[_i]), (PG8_LAS unsigned*)(lds + (bufoff) + ldsw + _i * 8192), 16, 0, 0); } while (0)
; #define PG8_LDA(dst, b, h) do { _Pragma("unroll") for (int m = 0; m < 4; ++m) _Pragma("unroll") for (int k = 0; k < 2; ++k) dst[m][k] = *(const PG8_LAS bf16x8*)(lds + PG8_SA(b, h) + aoff + m * 2048 + k * 1024); } while (0)
; #define PG8_MMA(ai, bj, At, Bt) do { __builtin_amdgcn_s_setprio(1); _Pragma("unroll") for (int m = 0; m < 4; ++m) _Pragma("unroll") for (int n = 0; n < 2; ++n) _Pragma("unroll") for (int k = 0; k < 2; ++k) \
;         acc[ai][bj][m][n] = __builtin_amdgcn_mfma_f32_16x16x32_bf16(Bt[n][k], At[m][k], acc[ai][bj][m][n], 0, 0, 0); __builtin_amdgcn_s_setprio(0); } while (0)
; #define PG8_WAIT_V(n) asm volatile("s_waitcnt vmcnt(" #n ")" ::: "memory")
; #define PG8_WAIT_L(n) asm volatile("s_waitcnt lgkmcnt(" #n ")" ::: "memory")
; #define PG8_BAR __builtin_amdgcn_s_barrier()
; #define PG8_SCHED __builtin_amdgcn_sched_barrier(0)
; template <class Epi, class Sched, bool ALIGN_EPI = false, bool SP2 = false>
; __device__ __forceinline__ void gemm_phase(PG8_LAS unsigned char* lds, const Gemm g, const Sched& S, const Epi& E) {
;     ...
;             PG8_LDA(At, 1, 1); PG8_STAGE(PG8_SB(1, 0), b3, voffB); PG8_STAGE(PG8_SB(1, 1), b3 + hstepB, voffB); PG8_STAGE(PG8_SA(1, 0), a3, voffA);
;             PG8_WAIT_V(8); PG8_WAIT_L(0); PG8_BAR; PG8_MMA(1, 0, At, B0); PG8_MMA(1, 1, At, B1); PG8_BAR; PG8_SCHED;
	s_add_i32 s14, s45, s2
	v_lshl_add_u64 v[216:217], v[216:217], 0, s[8:9]
	s_mov_b32 m0, s14
	ds_read_b128 v[184:187], v154 offset:49152
	ds_read_b128 v[188:191], v154 offset:50176
	ds_read_b128 v[192:195], v154 offset:51200
	ds_read_b128 v[196:199], v154 offset:52224
	ds_read_b128 v[200:203], v154 offset:53248
	ds_read_b128 v[204:207], v154 offset:54272
	ds_read_b128 v[208:211], v154 offset:55296
	ds_read_b128 v[212:215], v154 offset:56320
	global_load_lds_dwordx4 v[216:217], off
	s_add_i32 m0, s14, 0x2000
	s_add_u32 s14, s18, 0x108080
	v_lshl_add_u64 v[216:217], v[218:219], 0, s[8:9]
	s_addc_u32 s15, s19, 0
	s_add_i32 s18, s46, s2
	global_load_lds_dwordx4 v[216:217], off
	v_lshl_add_u64 v[216:217], s[14:15], 0, v[134:135]
	s_mov_b32 m0, s18
	s_nop 0
	global_load_lds_dwordx4 v[216:217], off
	v_lshl_add_u64 v[216:217], s[14:15], 0, v[130:131]
	s_add_i32 m0, s18, 0x2000
	s_nop 0
	global_load_lds_dwordx4 v[216:217], off
	v_lshl_add_u64 v[216:217], v[220:221], 0, s[8:9]
	s_mov_b32 m0, s31
	s_nop 0
	global_load_lds_dwordx4 v[216:217], off
	v_lshl_add_u64 v[216:217], v[222:223], 0, s[8:9]
	s_mov_b32 m0, s33
	s_nop 0
	global_load_lds_dwordx4 v[216:217], off
	s_waitcnt vmcnt(8)
	s_waitcnt lgkmcnt(0)
	s_barrier
	s_setprio 1
	s_waitcnt lgkmcnt(0)
	v_mfma_f32_16x16x32_bf16 v[62:65], v[146:149], v[184:187], v[62:65]
	v_mfma_f32_16x16x32_bf16 v[62:65], v[156:159], v[188:191], v[62:65]
	v_mfma_f32_16x16x32_bf16 v[58:61], v[160:163], v[184:187], v[58:61]
	v_mfma_f32_16x16x32_bf16 v[58:61], v[164:167], v[188:191], v[58:61]
	v_mfma_f32_16x16x32_bf16 v[46:49], v[146:149], v[192:195], v[46:49]
	v_mfma_f32_16x16x32_bf16 v[46:49], v[156:159], v[196:199], v[46:49]
	v_mfma_f32_16x16x32_bf16 v[42:45], v[160:163], v[192:195], v[42:45]
	v_mfma_f32_16x16x32_bf16 v[42:45], v[164:167], v[196:199], v[42:45]
	v_mfma_f32_16x16x32_bf16 v[30:33], v[146:149], v[200:203], v[30:33]
	v_mfma_f32_16x16x32_bf16 v[30:33], v[156:159], v[204:207], v[30:33]
	v_mfma_f32_16x16x32_bf16 v[26:29], v[160:163], v[200:203], v[26:29]
	v_mfma_f32_16x16x32_bf16 v[26:29], v[164:167], v[204:207], v[26:29]
	v_mfma_f32_16x16x32_bf16 v[14:17], v[146:149], v[208:211], v[14:17]
	v_mfma_f32_16x16x32_bf16 v[14:17], v[156:159], v[212:215], v[14:17]
	v_mfma_f32_16x16x32_bf16 v[10:13], v[160:163], v[208:211], v[10:13]
	v_mfma_f32_16x16x32_bf16 v[10:13], v[164:167], v[212:215], v[10:13]
	s_setprio 0
	s_setprio 1
	v_mfma_f32_16x16x32_bf16 v[54:57], v[168:171], v[184:187], v[54:57]
	v_mfma_f32_16x16x32_bf16 v[54:57], v[172:175], v[188:191], v[54:57]
	v_mfma_f32_16x16x32_bf16 v[50:53], v[176:179], v[184:187], v[50:53]
	v_mfma_f32_16x16x32_bf16 v[50:53], v[180:183], v[188:191], v[50:53]
	v_mfma_f32_16x16x32_bf16 v[38:41], v[168:171], v[192:195], v[38:41]
	v_mfma_f32_16x16x32_bf16 v[38:41], v[172:175], v[196:199], v[38:41]
	v_mfma_f32_16x16x32_bf16 v[34:37], v[176:179], v[192:195], v[34:37]
	v_mfma_f32_16x16x32_bf16 v[34:37], v[180:183], v[196:199], v[34:37]
	v_mfma_f32_16x16x32_bf16 v[22:25], v[168:171], v[200:203], v[22:25]
	v_mfma_f32_16x16x32_bf16 v[22:25], v[172:175], v[204:207], v[22:25]
	v_mfma_f32_16x16x32_bf16 v[18:21], v[176:179], v[200:203], v[18:21]
	v_mfma_f32_16x16x32_bf16 v[18:21], v[180:183], v[204:207], v[18:21]
	v_mfma_f32_16x16x32_bf16 v[6:9], v[168:171], v[208:211], v[6:9]
	v_mfma_f32_16x16x32_bf16 v[6:9], v[172:175], v[212:215], v[6:9]
	v_mfma_f32_16x16x32_bf16 v[2:5], v[176:179], v[208:211], v[2:5]
	v_mfma_f32_16x16x32_bf16 v[2:5], v[180:183], v[212:215], v[2:5]
	s_setprio 0
	s_barrier
	s_add_i32 s44, s44, 2
	s_add_u32 s42, s42, 0x100
	s_addc_u32 s43, s43, 0
	s_cmp_gt_u32 s44, 61
	s_mov_b64 s[14:15], s[16:17]
	s_cbranch_scc0 .LBB0_1889
	s_and_b64 vcc, exec, s[10:11]
	s_cbranch_vccz .LBB0_1892
	s_barrier

; #define PG8_STAGE(bufoff, gbase, voff) do { _Pragma("unroll") for (int _i = 0; _i < 2; ++_i) \
;         __builtin_amdgcn_global_load_lds((const unsigned*)((const char*)(gbase) + (voff)[_i]), (PG8_LAS unsigned*)(lds + (bufoff) + ldsw + _i * 8192), 16, 0, 0); } while (0)
; #define PG8_LDA(dst, b, h) do { _Pragma("unroll") for (int m = 0; m < 4; ++m) _Pragma("unroll") for (int k = 0; k < 2; ++k) dst[m][k] = *(const PG8_LAS bf16x8*)(lds + PG8_SA(b, h) + aoff + m * 2048 + k * 1024); } while (0)
; #define PG8_LDB(dst, b, h) do { _Pragma("unroll") for (int n = 0; n < 2; ++n) _Pragma("unroll") for (int k = 0; k < 2; ++k) dst[n][k] = *(const PG8_LAS bf16x8*)(lds + PG8_SB(b, h) + boff + n * 2048 + k * 1024); } while (0)
; #define PG8_MMA(ai, bj, At, Bt) do { __builtin_amdgcn_s_setprio(1); _Pragma("unroll") for (int m = 0; m < 4; ++m) _Pragma("unroll") for (int n = 0; n < 2; ++n) _Pragma("unroll") for (int k = 0; k < 2; ++k) \
;         acc[ai][bj][m][n] = __builtin_amdgcn_mfma_f32_16x16x32_bf16(Bt[n][k], At[m][k], acc[ai][bj][m][n], 0, 0, 0); __builtin_amdgcn_s_setprio(0); } while (0)
; #define PG8_WAIT_V(n) asm volatile("s_waitcnt vmcnt(" #n ")" ::: "memory")
; #define PG8_WAIT_L(n) asm volatile("s_waitcnt lgkmcnt(" #n ")" ::: "memory")
; #define PG8_BAR __builtin_amdgcn_s_barrier()
; #define PG8_SCHED __builtin_amdgcn_sched_barrier(0)
; template <class Epi, class Sched, bool ALIGN_EPI = false, bool SP2 = false>
; __device__ __forceinline__ void gemm_phase(PG8_LAS unsigned char* lds, const Gemm g, const Sched& S, const Epi& E) {
;     ...
;             PG8_LDB(B0, 0, 0); PG8_LDB(B1, 0, 1); PG8_SCHED; PG8_LDA(At, 0, 0); PG8_STAGE(PG8_SA(1, 1), a1 + hstep, voffA);
;             PG8_WAIT_V(8); PG8_WAIT_L(0); PG8_BAR; PG8_MMA(0, 0, At, B0); PG8_MMA(0, 1, At, B1); PG8_BAR; PG8_SCHED;
;             PG8_LDA(At, 0, 1); PG8_STAGE(PG8_SB(0, 0), b2, voffB); PG8_STAGE(PG8_SB(0, 1), b2 + hstepB, voffB); PG8_STAGE(PG8_SA(0, 0), a2, voffA);
;             PG8_WAIT_V(8); PG8_WAIT_L(0); PG8_BAR; PG8_MMA(1, 0, At, B0); PG8_MMA(1, 1, At, B1); PG8_BAR; PG8_SCHED;
.LBB0_2165:
	ds_read_b128 v[128:131], v167
	ds_read_b128 v[132:135], v167 offset:1024
	ds_read_b128 v[136:139], v167 offset:2048
	ds_read_b128 v[140:143], v167 offset:3072
	ds_read_b128 v[160:163], v168
	ds_read_b128 v[170:173], v168 offset:1024
	ds_read_b128 v[174:177], v168 offset:2048
	ds_read_b128 v[178:181], v168 offset:3072
	s_add_u32 s16, s14, 0x100
	s_addc_u32 s17, s15, 0
	s_cmpk_eq_i32 s57, 0xa8
	s_cselect_b32 s21, s5, s17
	s_cselect_b32 s20, s4, s16
	s_cselect_b32 s19, s13, s56
	s_cselect_b32 s18, s12, s55
	v_lshl_add_u64 v[214:215], s[14:15], 0, v[152:153]
	s_add_i32 m0, s25, 0xc000
	ds_read_b128 v[182:185], v169
	ds_read_b128 v[186:189], v169 offset:1024
	ds_read_b128 v[190:193], v169 offset:2048
	ds_read_b128 v[194:197], v169 offset:3072
	ds_read_b128 v[198:201], v169 offset:4096
	ds_read_b128 v[202:205], v169 offset:5120
	ds_read_b128 v[206:209], v169 offset:6144
	ds_read_b128 v[210:213], v169 offset:7168
	global_load_lds_dwordx4 v[214:215], off
	v_lshl_add_u64 v[214:215], s[14:15], 0, v[154:155]
	s_add_i32 m0, s25, 0xe000
	s_nop 0
	global_load_lds_dwordx4 v[214:215], off
	s_waitcnt vmcnt(8)
	s_waitcnt lgkmcnt(0)
	s_barrier
	s_setprio 1
	s_waitcnt lgkmcnt(0)
	v_mfma_f32_16x16x32_bf16 v[124:127], v[128:131], v[182:185], v[124:127]
	v_mfma_f32_16x16x32_bf16 v[124:127], v[132:135], v[186:189], v[124:127]
	v_mfma_f32_16x16x32_bf16 v[120:123], v[136:139], v[182:185], v[120:123]
	v_mfma_f32_16x16x32_bf16 v[120:123], v[140:143], v[186:189], v[120:123]
	v_mfma_f32_16x16x32_bf16 v[116:119], v[128:131], v[190:193], v[116:119]
	v_mfma_f32_16x16x32_bf16 v[116:119], v[132:135], v[194:197], v[116:119]
	v_mfma_f32_16x16x32_bf16 v[108:111], v[136:139], v[190:193], v[108:111]
	v_mfma_f32_16x16x32_bf16 v[108:111], v[140:143], v[194:197], v[108:111]
	v_mfma_f32_16x16x32_bf16 v[92:95], v[128:131], v[198:201], v[92:95]
	v_mfma_f32_16x16x32_bf16 v[92:95], v[132:135], v[202:205], v[92:95]
	v_mfma_f32_16x16x32_bf16 v[88:91], v[136:139], v[198:201], v[88:91]
	v_mfma_f32_16x16x32_bf16 v[88:91], v[140:143], v[202:205], v[88:91]
	v_mfma_f32_16x16x32_bf16 v[80:83], v[128:131], v[206:209], v[80:83]
	v_mfma_f32_16x16x32_bf16 v[80:83], v[132:135], v[210:213], v[80:83]
	v_mfma_f32_16x16x32_bf16 v[72:75], v[136:139], v[206:209], v[72:75]
	v_mfma_f32_16x16x32_bf16 v[72:75], v[140:143], v[210:213], v[72:75]
	s_setprio 0
	s_setprio 1
	v_mfma_f32_16x16x32_bf16 v[112:115], v[160:163], v[182:185], v[112:115]
	v_mfma_f32_16x16x32_bf16 v[112:115], v[170:173], v[186:189], v[112:115]
	v_mfma_f32_16x16x32_bf16 v[104:107], v[174:177], v[182:185], v[104:107]
	v_mfma_f32_16x16x32_bf16 v[104:107], v[178:181], v[186:189], v[104:107]
	v_mfma_f32_16x16x32_bf16 v[100:103], v[160:163], v[190:193], v[100:103]
	v_mfma_f32_16x16x32_bf16 v[100:103], v[170:173], v[194:197], v[100:103]
	v_mfma_f32_16x16x32_bf16 v[96:99], v[174:177], v[190:193], v[96:99]
	v_mfma_f32_16x16x32_bf16 v[96:99], v[178:181], v[194:197], v[96:99]
	v_mfma_f32_16x16x32_bf16 v[84:87], v[160:163], v[198:201], v[84:87]
	v_mfma_f32_16x16x32_bf16 v[84:87], v[170:173], v[202:205], v[84:87]
	v_mfma_f32_16x16x32_bf16 v[76:79], v[174:177], v[198:201], v[76:79]
	v_mfma_f32_16x16x32_bf16 v[76:79], v[178:181], v[202:205], v[76:79]
	v_mfma_f32_16x16x32_bf16 v[68:71], v[160:163], v[206:209], v[68:71]
	v_mfma_f32_16x16x32_bf16 v[68:71], v[170:173], v[210:213], v[68:71]
	v_mfma_f32_16x16x32_bf16 v[64:67], v[174:177], v[206:209], v[64:67]
	v_mfma_f32_16x16x32_bf16 v[64:67], v[178:181], v[210:213], v[64:67]
	s_setprio 0
	s_barrier
	s_add_i32 s14, s36, s24
	v_lshl_add_u64 v[214:215], s[18:19], 0, v[146:147]
	s_mov_b32 m0, s14
	ds_read_b128 v[182:185], v169 offset:16384
	ds_read_b128 v[186:189], v169 offset:17408
	ds_read_b128 v[190:193], v169 offset:18432
	ds_read_b128 v[194:197], v169 offset:19456
	ds_read_b128 v[198:201], v169 offset:20480
	ds_read_b128 v[202:205], v169 offset:21504
	ds_read_b128 v[206:209], v169 offset:22528
	ds_read_b128 v[210:213], v169 offset:23552
	global_load_lds_dwordx4 v[214:215], off
	s_add_i32 m0, s14, 0x2000
	s_add_u32 s14, s18, 0x2b0000
	v_lshl_add_u64 v[216:217], s[18:19], 0, v[150:151]
	s_addc_u32 s15, s19, 0
	s_add_i32 s58, s37, s24
	global_load_lds_dwordx4 v[216:217], off
	v_lshl_add_u64 v[218:219], s[14:15], 0, v[146:147]
	s_mov_b32 m0, s58
	v_lshl_add_u64 v[220:221], s[20:21], 0, v[148:149]
	global_load_lds_dwordx4 v[218:219], off
	v_lshl_add_u64 v[218:219], s[14:15], 0, v[150:151]
	s_add_i32 m0, s58, 0x2000
	s_nop 0
	global_load_lds_dwordx4 v[218:219], off
	v_lshl_add_u64 v[218:219], s[20:21], 0, v[144:145]
	s_mov_b32 m0, s25
	s_nop 0
	global_load_lds_dwordx4 v[218:219], off
	s_mov_b32 m0, s26
	s_nop 0
	global_load_lds_dwordx4 v[220:221], off
	s_waitcnt vmcnt(8)
	s_waitcnt lgkmcnt(0)
	s_barrier
; #define PG8_STAGE(bufoff, gbase, voff) do { _Pragma("unroll") for (int _i = 0; _i < 2; ++_i) \
;         __builtin_amdgcn_global_load_lds((const unsigned*)((const char*)(gbase) + (voff)[_i]), (PG8_LAS unsigned*)(lds + (bufoff) + ldsw + _i * 8192), 16, 0, 0); } while (0)
; #define PG8_LDA(dst, b, h) do { _Pragma("unroll") for (int m = 0; m < 4; ++m) _Pragma("unroll") for (int k = 0; k < 2; ++k) dst[m][k] = *(const PG8_LAS bf16x8*)(lds + PG8_SA(b, h) + aoff + m * 2048 + k * 1024); } while (0)
; #define PG8_LDB(dst, b, h) do { _Pragma("unroll") for (int n = 0; n < 2; ++n) _Pragma("unroll") for (int k = 0; k < 2; ++k) dst[n][k] = *(const PG8_LAS bf16x8*)(lds + PG8_SB(b, h) + boff + n * 2048 + k * 1024); } while (0)
; #define PG8_MMA(ai, bj, At, Bt) do { __builtin_amdgcn_s_setprio(1); _Pragma("unroll") for (int m = 0; m < 4; ++m) _Pragma("unroll") for (int n = 0; n < 2; ++n) _Pragma("unroll") for (int k = 0; k < 2; ++k) \
;         acc[ai][bj][m][n] = __builtin_amdgcn_mfma_f32_16x16x32_bf16(Bt[n][k], At[m][k], acc[ai][bj][m][n], 0, 0, 0); __builtin_amdgcn_s_setprio(0); } while (0)
; #define PG8_WAIT_V(n) asm volatile("s_waitcnt vmcnt(" #n ")" ::: "memory")
; #define PG8_WAIT_L(n) asm volatile("s_waitcnt lgkmcnt(" #n ")" ::: "memory")
; #define PG8_BAR __builtin_amdgcn_s_barrier()
; #define PG8_SCHED __builtin_amdgcn_sched_barrier(0)
; template <class Epi, class Sched, bool ALIGN_EPI = false, bool SP2 = false>
; __device__ __forceinline__ void gemm_phase(PG8_LAS unsigned char* lds, const Gemm g, const Sched& S, const Epi& E) {
;     ...
;             PG8_WAIT_V(8); PG8_WAIT_L(0); PG8_BAR; PG8_MMA(1, 0, At, B0); PG8_MMA(1, 1, At, B1); PG8_BAR; PG8_SCHED;
;             PG8_LDB(B0, 1, 0); PG8_LDB(B1, 1, 1); PG8_SCHED; PG8_LDA(At, 1, 0); PG8_STAGE(PG8_SA(0, 1), a2 + hstep, voffA);
;             PG8_WAIT_V(8); PG8_WAIT_L(0); PG8_BAR; PG8_MMA(0, 0, At, B0); PG8_MMA(0, 1, At, B1); PG8_BAR; PG8_SCHED;
	s_setprio 1
	s_waitcnt lgkmcnt(0)
	v_mfma_f32_16x16x32_bf16 v[60:63], v[128:131], v[182:185], v[60:63]
	v_mfma_f32_16x16x32_bf16 v[60:63], v[132:135], v[186:189], v[60:63]
	v_mfma_f32_16x16x32_bf16 v[56:59], v[136:139], v[182:185], v[56:59]
	v_mfma_f32_16x16x32_bf16 v[56:59], v[140:143], v[186:189], v[56:59]
	v_mfma_f32_16x16x32_bf16 v[48:51], v[128:131], v[190:193], v[48:51]
	v_mfma_f32_16x16x32_bf16 v[48:51], v[132:135], v[194:197], v[48:51]
	v_mfma_f32_16x16x32_bf16 v[40:43], v[136:139], v[190:193], v[40:43]
	v_mfma_f32_16x16x32_bf16 v[40:43], v[140:143], v[194:197], v[40:43]
	v_mfma_f32_16x16x32_bf16 v[28:31], v[128:131], v[198:201], v[28:31]
	v_mfma_f32_16x16x32_bf16 v[28:31], v[132:135], v[202:205], v[28:31]
	v_mfma_f32_16x16x32_bf16 v[24:27], v[136:139], v[198:201], v[24:27]
	v_mfma_f32_16x16x32_bf16 v[24:27], v[140:143], v[202:205], v[24:27]
	v_mfma_f32_16x16x32_bf16 v[20:23], v[128:131], v[206:209], v[20:23]
	v_mfma_f32_16x16x32_bf16 v[20:23], v[132:135], v[210:213], v[20:23]
	v_mfma_f32_16x16x32_bf16 v[12:15], v[136:139], v[206:209], v[12:15]
	v_mfma_f32_16x16x32_bf16 v[12:15], v[140:143], v[210:213], v[12:15]
	s_setprio 0
	s_setprio 1
	v_mfma_f32_16x16x32_bf16 v[52:55], v[160:163], v[182:185], v[52:55]
	v_mfma_f32_16x16x32_bf16 v[52:55], v[170:173], v[186:189], v[52:55]
	v_mfma_f32_16x16x32_bf16 v[44:47], v[174:177], v[182:185], v[44:47]
	v_mfma_f32_16x16x32_bf16 v[44:47], v[178:181], v[186:189], v[44:47]
	v_mfma_f32_16x16x32_bf16 v[36:39], v[160:163], v[190:193], v[36:39]
	v_mfma_f32_16x16x32_bf16 v[36:39], v[170:173], v[194:197], v[36:39]
	v_mfma_f32_16x16x32_bf16 v[32:35], v[174:177], v[190:193], v[32:35]
	v_mfma_f32_16x16x32_bf16 v[32:35], v[178:181], v[194:197], v[32:35]
	v_mfma_f32_16x16x32_bf16 v[16:19], v[160:163], v[198:201], v[16:19]
	v_mfma_f32_16x16x32_bf16 v[16:19], v[170:173], v[202:205], v[16:19]
	v_mfma_f32_16x16x32_bf16 v[8:11], v[174:177], v[198:201], v[8:11]
	v_mfma_f32_16x16x32_bf16 v[8:11], v[178:181], v[202:205], v[8:11]
	v_mfma_f32_16x16x32_bf16 v[4:7], v[160:163], v[206:209], v[4:7]
	v_mfma_f32_16x16x32_bf16 v[4:7], v[170:173], v[210:213], v[4:7]
	v_mfma_f32_16x16x32_bf16 v[0:3], v[174:177], v[206:209], v[0:3]
	v_mfma_f32_16x16x32_bf16 v[0:3], v[178:181], v[210:213], v[0:3]
	s_setprio 0
	s_barrier
	s_add_i32 s58, 0, 0x18000
	s_add_i32 s59, 0, 0x1c000
	v_add_u32_e32 v140, s58, v165
	v_add_u32_e32 v178, s59, v165
	ds_read_b128 v[128:131], v140
	ds_read_b128 v[132:135], v140 offset:1024
	ds_read_b128 v[136:139], v140 offset:2048
	ds_read_b128 v[140:143], v140 offset:3072
	ds_read_b128 v[160:163], v178
	ds_read_b128 v[170:173], v178 offset:1024
	ds_read_b128 v[174:177], v178 offset:2048
	ds_read_b128 v[178:181], v178 offset:3072
	s_add_u32 s14, s20, 0x2b0000
	s_addc_u32 s15, s21, 0
	s_mov_b32 m0, s27
	v_lshl_add_u64 v[222:223], s[14:15], 0, v[144:145]
	ds_read_b128 v[182:185], v169 offset:32768
	ds_read_b128 v[186:189], v169 offset:33792
	ds_read_b128 v[190:193], v169 offset:34816
	ds_read_b128 v[194:197], v169 offset:35840
	ds_read_b128 v[198:201], v169 offset:36864
	ds_read_b128 v[202:205], v169 offset:37888
	ds_read_b128 v[206:209], v169 offset:38912
	ds_read_b128 v[210:213], v169 offset:39936
	global_load_lds_dwordx4 v[222:223], off
	v_lshl_add_u64 v[222:223], s[14:15], 0, v[148:149]
	s_mov_b32 m0, s28
	s_nop 0
	global_load_lds_dwordx4 v[222:223], off
	s_waitcnt vmcnt(8)
	s_waitcnt lgkmcnt(0)
	s_barrier
	s_setprio 1
	s_waitcnt lgkmcnt(0)
	v_mfma_f32_16x16x32_bf16 v[124:127], v[128:131], v[182:185], v[124:127]
	v_mfma_f32_16x16x32_bf16 v[124:127], v[132:135], v[186:189], v[124:127]
	v_mfma_f32_16x16x32_bf16 v[120:123], v[136:139], v[182:185], v[120:123]
	v_mfma_f32_16x16x32_bf16 v[120:123], v[140:143], v[186:189], v[120:123]
	v_mfma_f32_16x16x32_bf16 v[116:119], v[128:131], v[190:193], v[116:119]
	v_mfma_f32_16x16x32_bf16 v[116:119], v[132:135], v[194:197], v[116:119]
	v_mfma_f32_16x16x32_bf16 v[108:111], v[136:139], v[190:193], v[108:111]
	v_mfma_f32_16x16x32_bf16 v[108:111], v[140:143], v[194:197], v[108:111]
	v_mfma_f32_16x16x32_bf16 v[92:95], v[128:131], v[198:201], v[92:95]
	v_mfma_f32_16x16x32_bf16 v[92:95], v[132:135], v[202:205], v[92:95]
	v_mfma_f32_16x16x32_bf16 v[88:91], v[136:139], v[198:201], v[88:91]
	v_mfma_f32_16x16x32_bf16 v[88:91], v[140:143], v[202:205], v[88:91]
	v_mfma_f32_16x16x32_bf16 v[80:83], v[128:131], v[206:209], v[80:83]
	v_mfma_f32_16x16x32_bf16 v[80:83], v[132:135], v[210:213], v[80:83]
	v_mfma_f32_16x16x32_bf16 v[72:75], v[136:139], v[206:209], v[72:75]
	v_mfma_f32_16x16x32_bf16 v[72:75], v[140:143], v[210:213], v[72:75]
	s_setprio 0
	s_setprio 1
	v_mfma_f32_16x16x32_bf16 v[112:115], v[160:163], v[182:185], v[112:115]
	v_mfma_f32_16x16x32_bf16 v[112:115], v[170:173], v[186:189], v[112:115]
	v_mfma_f32_16x16x32_bf16 v[104:107], v[174:177], v[182:185], v[104:107]
	v_mfma_f32_16x16x32_bf16 v[104:107], v[178:181], v[186:189], v[104:107]
	v_mfma_f32_16x16x32_bf16 v[100:103], v[160:163], v[190:193], v[100:103]
	v_mfma_f32_16x16x32_bf16 v[100:103], v[170:173], v[194:197], v[100:103]
	v_mfma_f32_16x16x32_bf16 v[96:99], v[174:177], v[190:193], v[96:99]
	v_mfma_f32_16x16x32_bf16 v[96:99], v[178:181], v[194:197], v[96:99]
	v_mfma_f32_16x16x32_bf16 v[84:87], v[160:163], v[198:201], v[84:87]
	v_mfma_f32_16x16x32_bf16 v[84:87], v[170:173], v[202:205], v[84:87]
	v_mfma_f32_16x16x32_bf16 v[76:79], v[174:177], v[198:201], v[76:79]
	v_mfma_f32_16x16x32_bf16 v[76:79], v[178:181], v[202:205], v[76:79]
	v_mfma_f32_16x16x32_bf16 v[68:71], v[160:163], v[206:209], v[68:71]
	v_mfma_f32_16x16x32_bf16 v[68:71], v[170:173], v[210:213], v[68:71]
	v_mfma_f32_16x16x32_bf16 v[64:67], v[174:177], v[206:209], v[64:67]
	v_mfma_f32_16x16x32_bf16 v[64:67], v[178:181], v[210:213], v[64:67]
	s_setprio 0
	s_barrier
; #define PG8_STAGE(bufoff, gbase, voff) do { _Pragma("unroll") for (int _i = 0; _i < 2; ++_i) \
;         __builtin_amdgcn_global_load_lds((const unsigned*)((const char*)(gbase) + (voff)[_i]), (PG8_LAS unsigned*)(lds + (bufoff) + ldsw + _i * 8192), 16, 0, 0); } while (0)
; #define PG8_LDA(dst, b, h) do { _Pragma("unroll") for (int m = 0; m < 4; ++m) _Pragma("unroll") for (int k = 0; k < 2; ++k) dst[m][k] = *(const PG8_LAS bf16x8*)(lds + PG8_SA(b, h) + aoff + m * 2048 + k * 1024); } while (0)
; #define PG8_MMA(ai, bj, At, Bt) do { __builtin_amdgcn_s_setprio(1); _Pragma("unroll") for (int m = 0; m < 4; ++m) _Pragma("unroll") for (int n = 0; n < 2; ++n) _Pragma("unroll") for (int k = 0; k < 2; ++k) \
;         acc[ai][bj][m][n] = __builtin_amdgcn_mfma_f32_16x16x32_bf16(Bt[n][k], At[m][k], acc[ai][bj][m][n], 0, 0, 0); __builtin_amdgcn_s_setprio(0); } while (0)
; #define PG8_WAIT_V(n) asm volatile("s_waitcnt vmcnt(" #n ")" ::: "memory")
; #define PG8_WAIT_L(n) asm volatile("s_waitcnt lgkmcnt(" #n ")" ::: "memory")
; #define PG8_BAR __builtin_amdgcn_s_barrier()
; #define PG8_SCHED __builtin_amdgcn_sched_barrier(0)
; template <class Epi, class Sched, bool ALIGN_EPI = false, bool SP2 = false>
; __device__ __forceinline__ void gemm_phase(PG8_LAS unsigned char* lds, const Gemm g, const Sched& S, const Epi& E) {
;     ...
;             PG8_LDA(At, 1, 1); PG8_STAGE(PG8_SB(1, 0), b3, voffB); PG8_STAGE(PG8_SB(1, 1), b3 + hstepB, voffB); PG8_STAGE(PG8_SA(1, 0), a3, voffA);
;             PG8_WAIT_V(8); PG8_WAIT_L(0); PG8_BAR; PG8_MMA(1, 0, At, B0); PG8_MMA(1, 1, At, B1); PG8_BAR; PG8_SCHED;
	s_add_i32 s14, s58, s24
	v_lshl_add_u64 v[214:215], v[214:215], 0, s[8:9]
	s_mov_b32 m0, s14
	ds_read_b128 v[182:185], v169 offset:49152
	ds_read_b128 v[186:189], v169 offset:50176
	ds_read_b128 v[190:193], v169 offset:51200
	ds_read_b128 v[194:197], v169 offset:52224
	ds_read_b128 v[198:201], v169 offset:53248
	ds_read_b128 v[202:205], v169 offset:54272
	ds_read_b128 v[206:209], v169 offset:55296
	ds_read_b128 v[210:213], v169 offset:56320
	global_load_lds_dwordx4 v[214:215], off
	s_add_i32 m0, s14, 0x2000
	s_add_u32 s14, s18, 0x2b0080
	v_lshl_add_u64 v[214:215], v[216:217], 0, s[8:9]
	s_addc_u32 s15, s19, 0
	s_add_i32 s18, s59, s24
	global_load_lds_dwordx4 v[214:215], off
	v_lshl_add_u64 v[214:215], s[14:15], 0, v[146:147]
	s_mov_b32 m0, s18
	s_nop 0
	global_load_lds_dwordx4 v[214:215], off
	v_lshl_add_u64 v[214:215], s[14:15], 0, v[150:151]
	s_add_i32 m0, s18, 0x2000
	s_nop 0
	global_load_lds_dwordx4 v[214:215], off
	v_lshl_add_u64 v[214:215], v[218:219], 0, s[8:9]
	s_mov_b32 m0, s33
	s_nop 0
	global_load_lds_dwordx4 v[214:215], off
	v_lshl_add_u64 v[214:215], v[220:221], 0, s[8:9]
	s_mov_b32 m0, s34
	s_nop 0
	global_load_lds_dwordx4 v[214:215], off
	s_waitcnt vmcnt(8)
	s_waitcnt lgkmcnt(0)
	s_barrier
	s_setprio 1
	s_waitcnt lgkmcnt(0)
	v_mfma_f32_16x16x32_bf16 v[60:63], v[128:131], v[182:185], v[60:63]
	v_mfma_f32_16x16x32_bf16 v[60:63], v[132:135], v[186:189], v[60:63]
	v_mfma_f32_16x16x32_bf16 v[56:59], v[136:139], v[182:185], v[56:59]
	v_mfma_f32_16x16x32_bf16 v[56:59], v[140:143], v[186:189], v[56:59]
	v_mfma_f32_16x16x32_bf16 v[48:51], v[128:131], v[190:193], v[48:51]
	v_mfma_f32_16x16x32_bf16 v[48:51], v[132:135], v[194:197], v[48:51]
	v_mfma_f32_16x16x32_bf16 v[40:43], v[136:139], v[190:193], v[40:43]
	v_mfma_f32_16x16x32_bf16 v[40:43], v[140:143], v[194:197], v[40:43]
	v_mfma_f32_16x16x32_bf16 v[28:31], v[128:131], v[198:201], v[28:31]
	v_mfma_f32_16x16x32_bf16 v[28:31], v[132:135], v[202:205], v[28:31]
	v_mfma_f32_16x16x32_bf16 v[24:27], v[136:139], v[198:201], v[24:27]
	v_mfma_f32_16x16x32_bf16 v[24:27], v[140:143], v[202:205], v[24:27]
	v_mfma_f32_16x16x32_bf16 v[20:23], v[128:131], v[206:209], v[20:23]
	v_mfma_f32_16x16x32_bf16 v[20:23], v[132:135], v[210:213], v[20:23]
	v_mfma_f32_16x16x32_bf16 v[12:15], v[136:139], v[206:209], v[12:15]
	v_mfma_f32_16x16x32_bf16 v[12:15], v[140:143], v[210:213], v[12:15]
	s_setprio 0
	s_setprio 1
	v_mfma_f32_16x16x32_bf16 v[52:55], v[160:163], v[182:185], v[52:55]
	v_mfma_f32_16x16x32_bf16 v[52:55], v[170:173], v[186:189], v[52:55]
	v_mfma_f32_16x16x32_bf16 v[44:47], v[174:177], v[182:185], v[44:47]
	v_mfma_f32_16x16x32_bf16 v[44:47], v[178:181], v[186:189], v[44:47]
	v_mfma_f32_16x16x32_bf16 v[36:39], v[160:163], v[190:193], v[36:39]
	v_mfma_f32_16x16x32_bf16 v[36:39], v[170:173], v[194:197], v[36:39]
	v_mfma_f32_16x16x32_bf16 v[32:35], v[174:177], v[190:193], v[32:35]
	v_mfma_f32_16x16x32_bf16 v[32:35], v[178:181], v[194:197], v[32:35]
	v_mfma_f32_16x16x32_bf16 v[16:19], v[160:163], v[198:201], v[16:19]
	v_mfma_f32_16x16x32_bf16 v[16:19], v[170:173], v[202:205], v[16:19]
	v_mfma_f32_16x16x32_bf16 v[8:11], v[174:177], v[198:201], v[8:11]
	v_mfma_f32_16x16x32_bf16 v[8:11], v[178:181], v[202:205], v[8:11]
	v_mfma_f32_16x16x32_bf16 v[4:7], v[160:163], v[206:209], v[4:7]
	v_mfma_f32_16x16x32_bf16 v[4:7], v[170:173], v[210:213], v[4:7]
	v_mfma_f32_16x16x32_bf16 v[0:3], v[174:177], v[206:209], v[0:3]
	v_mfma_f32_16x16x32_bf16 v[0:3], v[178:181], v[210:213], v[0:3]
	s_setprio 0
	s_barrier
	s_add_i32 s57, s57, 2
	s_add_u32 s55, s55, 0x100
	s_addc_u32 s56, s56, 0
	s_cmpk_gt_u32 s57, 0xa9
	s_mov_b64 s[14:15], s[16:17]
	s_cbranch_scc0 .LBB0_2165
	s_and_b64 vcc, exec, s[10:11]
	s_cbranch_vccz .LBB0_2168
	s_barrier
